# norm-residual epilogue step 5: f32 out stores rearranged to full 128-B lines (adjacent-row lanes exchange n0/n1 quads via DPP), on top of xn widening
# speedup vs baseline: 1.0117x; 1.0027x over previous
; __device__ __forceinline__ unsigned cvt_pk_bf16(float lo, float hi) { unsigned r; asm volatile("v_cvt_pk_bf16_f32 %0, %1, %2" : "=v"(r) : "v"(lo), "v"(hi)); return r; }
;     __device__ __forceinline__ void fused(f32x4 (&acc)[2][2][4][2], const Unit& u, int wr, int wc, int fr, int fq, PG8_LAS unsigned char* lds, int wid, int lane) const {
;     ...
;         asm volatile("s_waitcnt lgkmcnt(0)" ::: "memory"); __builtin_amdgcn_s_barrier(); asm volatile("" ::: "memory");
;         f32x4 g2v[2][2];
; #pragma unroll
;         for (int bj = 0; bj < 2; ++bj)
; #pragma unroll
;             for (int n = 0; n < 2; ++n) g2v[bj][n] = *(const f32x4*)(g2 + col0 + bj * HALF + n * 16);
; #pragma unroll
;         for (int ai = 0; ai < 2; ++ai)
; #pragma unroll
;             for (int m = 0; m < 4; ++m) { const int r = ai * HALF + wr * 64 + m * 16 + fr; const f32x2v sr = S[r]; const size_t off = (size_t)(u.pm * BM + r) * 1024 + col0;
; #pragma unroll
;                 for (int bj = 0; bj < 2; ++bj)
; #pragma unroll
;                     for (int n = 0; n < 2; ++n) { const f32x4 bs = *(const f32x4*)(base + off + bj * HALF + n * 16); const f32x4 x1 = bs + acc[ai][bj][m][n] * sr.x * gv[bj][n];
;                         const f32x4 o = x1 * sr.y * g2v[bj][n]; u32x2 w; w.x = cvt_pk_bf16(o[0], o[1]); w.y = cvt_pk_bf16(o[2], o[3]);
;                         if (!dry || x1[0] == 1.2345e38f) { *(f32x4*)(out + off + bj * HALF + n * 16) = x1; *(u32x2*)(xn + off + bj * HALF + n * 16) = w; } }
;                 if (m & 1) asm volatile("" ::: "memory"); }
.LBB0_858:
	s_or_b64 exec, exec, s[6:7]
	v_and_b32_e32 v238, 1, v228
	v_sub_u32_e32 v238, 0, v238
	v_and_b32_e32 v252, 0xfffff040, v238
	v_add_u32_e32 v252, 0x800, v252
	v_mov_b32_e32 v253, v238
	v_and_b32_e32 v224, 63, v228
	v_lshrrev_b32_e32 v224, 4, v224
	v_lshlrev_b32_e32 v224, 3, v224
	v_mov_b32_e32 v225, 0
	v_lshl_add_u64 v[148:149], v[34:35], 2, s[28:29]
	s_mov_b64 s[4:5], 0x2000
	s_waitcnt lgkmcnt(0)
	v_lshl_add_u64 v[150:151], v[148:149], 0, s[4:5]
	v_add_co_u32_e32 v148, vcc, 0x2000, v148
	s_waitcnt lgkmcnt(0)
	s_barrier
	s_nop 0
	v_addc_co_u32_e32 v149, vcc, 0, v149, vcc
	global_load_dwordx4 v[160:163], v[148:149], off
	global_load_dwordx4 v[156:159], v[150:151], off offset:64
	global_load_dwordx4 v[152:155], v[150:151], off offset:512
	s_nop 0
	global_load_dwordx4 v[148:151], v[150:151], off offset:576
	v_lshl_add_u32 v33, v237, 3, 0
	global_load_dwordx4 v[208:211], v[164:165], off
	ds_read_b64 v[206:207], v33 offset:16384
	v_lshlrev_b64 v[166:167], 10, v[166:167]
	s_add_u32 s6, s22, 0xe300000
	v_lshl_add_u64 v[166:167], v[166:167], 0, v[34:35]
	s_addc_u32 s7, s23, 0
	s_waitcnt lgkmcnt(0)
	v_pk_mul_f32 v[146:147], v[146:147], v[206:207] op_sel_hi:[1,0]
	v_pk_mul_f32 v[144:145], v[144:145], v[206:207] op_sel_hi:[1,0]
	v_pk_mul_f32 v[140:141], v[140:141], v[206:207] op_sel_hi:[1,0]
	v_pk_mul_f32 v[142:143], v[142:143], v[206:207] op_sel_hi:[1,0]
	v_pk_mul_f32 v[136:137], v[136:137], v[206:207] op_sel_hi:[1,0]
	v_pk_mul_f32 v[138:139], v[138:139], v[206:207] op_sel_hi:[1,0]
	v_pk_mul_f32 v[132:133], v[132:133], v[206:207] op_sel_hi:[1,0]
	v_pk_mul_f32 v[134:135], v[134:135], v[206:207] op_sel_hi:[1,0]
	s_waitcnt vmcnt(0)
	v_pk_fma_f32 v[144:145], v[116:117], v[144:145], v[208:209]
	v_pk_fma_f32 v[146:147], v[118:119], v[146:147], v[210:211]
	v_pk_mul_f32 v[208:209], v[206:207], v[144:145] op_sel:[1,0]
	v_pk_mul_f32 v[210:211], v[206:207], v[146:147] op_sel:[1,0]
	v_pk_mul_f32 v[208:209], v[160:161], v[208:209]
	v_pk_mul_f32 v[210:211], v[162:163], v[210:211]
	v_cvt_pk_bf16_f32 v208, v208, v209
	s_nop 0
	v_cvt_pk_bf16_f32 v209, v210, v211
	v_lshl_add_u64 v[210:211], v[166:167], 2, s[20:21]
	v_lshl_add_u64 v[166:167], v[166:167], 1, s[6:7]
	v_mov_b32_e32 v248, v144
	v_mov_b32_e32 v249, v145
	v_mov_b32_e32 v250, v146
	v_mov_b32_e32 v251, v147
	v_mov_b32_e32 v220, v208
	v_mov_b32_e32 v221, v209
	global_load_dwordx4 v[144:147], v[164:165], off offset:64
	s_waitcnt vmcnt(0)
	v_pk_fma_f32 v[140:141], v[104:105], v[140:141], v[144:145]
	v_pk_fma_f32 v[142:143], v[106:107], v[142:143], v[146:147]
	v_pk_mul_f32 v[144:145], v[206:207], v[140:141] op_sel:[1,0]
	v_pk_mul_f32 v[146:147], v[206:207], v[142:143] op_sel:[1,0]
	v_pk_mul_f32 v[144:145], v[156:157], v[144:145]
	v_pk_mul_f32 v[146:147], v[158:159], v[146:147]
	v_cvt_pk_bf16_f32 v144, v144, v145
	s_nop 0
	v_cvt_pk_bf16_f32 v145, v146, v147
	v_bfi_b32 v240, v238, v248, v140
	v_bfi_b32 v241, v238, v249, v141
	v_bfi_b32 v242, v238, v250, v142
	v_bfi_b32 v243, v238, v251, v143
	v_lshl_add_u64 v[216:217], v[210:211], 0, v[252:253]
	s_nop 0
	v_mov_b32_dpp v244, v240 quad_perm:[1,0,3,2] row_mask:0xf bank_mask:0xf
	v_mov_b32_dpp v245, v241 quad_perm:[1,0,3,2] row_mask:0xf bank_mask:0xf
	v_mov_b32_dpp v246, v242 quad_perm:[1,0,3,2] row_mask:0xf bank_mask:0xf
	v_mov_b32_dpp v247, v243 quad_perm:[1,0,3,2] row_mask:0xf bank_mask:0xf
	v_bfi_b32 v248, v238, v244, v248
	v_bfi_b32 v249, v238, v245, v249
	v_bfi_b32 v250, v238, v246, v250
	v_bfi_b32 v251, v238, v247, v251
	v_bfi_b32 v244, v238, v140, v244
	v_bfi_b32 v245, v238, v141, v245
	v_bfi_b32 v246, v238, v142, v246
	v_bfi_b32 v247, v238, v143, v247
	global_store_dwordx4 v[216:217], v[248:251], off offset:-2048
	global_store_dwordx4 v[216:217], v[244:247], off offset:2048
	v_mov_b32_e32 v222, v144
	v_mov_b32_e32 v223, v145
	v_lshl_add_u64 v[226:227], v[166:167], 0, v[224:225]
	s_nop 0
	v_permlane32_swap_b32_e32 v220, v222
	v_permlane32_swap_b32_e32 v221, v223
	s_nop 1
	v_permlane16_swap_b32_e32 v220, v222
	v_permlane16_swap_b32_e32 v221, v223
	global_store_dwordx4 v[226:227], v[220:223], off
	global_load_dwordx4 v[140:143], v[164:165], off offset:512
	s_waitcnt vmcnt(0)
	v_pk_fma_f32 v[136:137], v[100:101], v[136:137], v[140:141]
	v_pk_fma_f32 v[138:139], v[102:103], v[138:139], v[142:143]
	v_pk_mul_f32 v[140:141], v[206:207], v[136:137] op_sel:[1,0]
	v_pk_mul_f32 v[142:143], v[206:207], v[138:139] op_sel:[1,0]
	v_pk_mul_f32 v[140:141], v[152:153], v[140:141]
	v_pk_mul_f32 v[142:143], v[154:155], v[142:143]
	v_cvt_pk_bf16_f32 v140, v140, v141
	s_nop 0
	v_cvt_pk_bf16_f32 v141, v142, v143
	v_mov_b32_e32 v248, v136
	v_mov_b32_e32 v249, v137
	v_mov_b32_e32 v250, v138
	v_mov_b32_e32 v251, v139
	v_mov_b32_e32 v220, v140
	v_mov_b32_e32 v221, v141
	global_load_dwordx4 v[136:139], v[164:165], off offset:576
	s_waitcnt vmcnt(0)
; __device__ __forceinline__ unsigned cvt_pk_bf16(float lo, float hi) { unsigned r; asm volatile("v_cvt_pk_bf16_f32 %0, %1, %2" : "=v"(r) : "v"(lo), "v"(hi)); return r; }
;     __device__ __forceinline__ void fused(f32x4 (&acc)[2][2][4][2], const Unit& u, int wr, int wc, int fr, int fq, PG8_LAS unsigned char* lds, int wid, int lane) const {
;     ...
;         for (int ai = 0; ai < 2; ++ai)
; #pragma unroll
;             for (int m = 0; m < 4; ++m) { const int r = ai * HALF + wr * 64 + m * 16 + fr; const f32x2v sr = S[r]; const size_t off = (size_t)(u.pm * BM + r) * 1024 + col0;
; #pragma unroll
;                 for (int bj = 0; bj < 2; ++bj)
; #pragma unroll
;                     for (int n = 0; n < 2; ++n) { const f32x4 bs = *(const f32x4*)(base + off + bj * HALF + n * 16); const f32x4 x1 = bs + acc[ai][bj][m][n] * sr.x * gv[bj][n];
;                         const f32x4 o = x1 * sr.y * g2v[bj][n]; u32x2 w; w.x = cvt_pk_bf16(o[0], o[1]); w.y = cvt_pk_bf16(o[2], o[3]);
;                         if (!dry || x1[0] == 1.2345e38f) { *(f32x4*)(out + off + bj * HALF + n * 16) = x1; *(u32x2*)(xn + off + bj * HALF + n * 16) = w; } }
;                 if (m & 1) asm volatile("" ::: "memory"); }
	v_pk_fma_f32 v[132:133], v[92:93], v[132:133], v[136:137]
	v_pk_fma_f32 v[134:135], v[94:95], v[134:135], v[138:139]
	v_pk_mul_f32 v[136:137], v[206:207], v[132:133] op_sel:[1,0]
	v_pk_mul_f32 v[138:139], v[206:207], v[134:135] op_sel:[1,0]
	v_pk_mul_f32 v[136:137], v[148:149], v[136:137]
	v_pk_mul_f32 v[138:139], v[150:151], v[138:139]
	v_cvt_pk_bf16_f32 v136, v136, v137
	s_nop 0
	v_cvt_pk_bf16_f32 v137, v138, v139
	v_bfi_b32 v240, v238, v248, v132
	v_bfi_b32 v241, v238, v249, v133
	v_bfi_b32 v242, v238, v250, v134
	v_bfi_b32 v243, v238, v251, v135
	v_lshl_add_u64 v[216:217], v[210:211], 0, v[252:253]
	s_nop 0
	v_mov_b32_dpp v244, v240 quad_perm:[1,0,3,2] row_mask:0xf bank_mask:0xf
	v_mov_b32_dpp v245, v241 quad_perm:[1,0,3,2] row_mask:0xf bank_mask:0xf
	v_mov_b32_dpp v246, v242 quad_perm:[1,0,3,2] row_mask:0xf bank_mask:0xf
	v_mov_b32_dpp v247, v243 quad_perm:[1,0,3,2] row_mask:0xf bank_mask:0xf
	v_bfi_b32 v248, v238, v244, v248
	v_bfi_b32 v249, v238, v245, v249
	v_bfi_b32 v250, v238, v246, v250
	v_bfi_b32 v251, v238, v247, v251
	v_bfi_b32 v244, v238, v132, v244
	v_bfi_b32 v245, v238, v133, v245
	v_bfi_b32 v246, v238, v134, v246
	v_bfi_b32 v247, v238, v135, v247
	global_store_dwordx4 v[216:217], v[248:251], off offset:-1536
	global_store_dwordx4 v[216:217], v[244:247], off offset:2560
	v_mov_b32_e32 v222, v136
	v_mov_b32_e32 v223, v137
	v_lshl_add_u64 v[226:227], v[166:167], 0, v[224:225]
	s_nop 0
	v_permlane32_swap_b32_e32 v220, v222
	v_permlane32_swap_b32_e32 v221, v223
	s_nop 1
	v_permlane16_swap_b32_e32 v220, v222
	v_permlane16_swap_b32_e32 v221, v223
	global_store_dwordx4 v[226:227], v[220:223], off offset:256
	ds_read_b64 v[136:137], v33 offset:16512
	v_lshlrev_b64 v[132:133], 10, v[170:171]
	v_lshl_add_u64 v[138:139], v[132:133], 0, v[34:35]
	global_load_dwordx4 v[132:135], v[168:169], off
	s_waitcnt lgkmcnt(0)
	v_pk_mul_f32 v[130:131], v[130:131], v[136:137] op_sel_hi:[1,0]
	v_pk_mul_f32 v[128:129], v[128:129], v[136:137] op_sel_hi:[1,0]
	v_pk_mul_f32 v[124:125], v[124:125], v[136:137] op_sel_hi:[1,0]
	v_pk_mul_f32 v[126:127], v[126:127], v[136:137] op_sel_hi:[1,0]
	v_pk_mul_f32 v[120:121], v[120:121], v[136:137] op_sel_hi:[1,0]
	v_pk_mul_f32 v[122:123], v[122:123], v[136:137] op_sel_hi:[1,0]
	v_pk_mul_f32 v[112:113], v[112:113], v[136:137] op_sel_hi:[1,0]
	v_pk_mul_f32 v[114:115], v[114:115], v[136:137] op_sel_hi:[1,0]
	s_waitcnt vmcnt(0)
	v_pk_fma_f32 v[128:129], v[116:117], v[128:129], v[132:133]
	v_pk_fma_f32 v[130:131], v[118:119], v[130:131], v[134:135]
	v_pk_mul_f32 v[132:133], v[136:137], v[128:129] op_sel:[1,0]
	v_pk_mul_f32 v[134:135], v[136:137], v[130:131] op_sel:[1,0]
	v_pk_mul_f32 v[132:133], v[160:161], v[132:133]
	v_pk_mul_f32 v[134:135], v[162:163], v[134:135]
	v_cvt_pk_bf16_f32 v132, v132, v133
	s_nop 0
	v_cvt_pk_bf16_f32 v133, v134, v135
	v_lshl_add_u64 v[134:135], v[138:139], 2, s[20:21]
	v_lshl_add_u64 v[138:139], v[138:139], 1, s[6:7]
	v_mov_b32_e32 v248, v128
	v_mov_b32_e32 v249, v129
	v_mov_b32_e32 v250, v130
	v_mov_b32_e32 v251, v131
	v_mov_b32_e32 v220, v132
	v_mov_b32_e32 v221, v133
	global_load_dwordx4 v[128:131], v[168:169], off offset:64
	s_waitcnt vmcnt(0)
	v_pk_fma_f32 v[124:125], v[104:105], v[124:125], v[128:129]
	v_pk_fma_f32 v[126:127], v[106:107], v[126:127], v[130:131]
	v_pk_mul_f32 v[128:129], v[136:137], v[124:125] op_sel:[1,0]
	v_pk_mul_f32 v[130:131], v[136:137], v[126:127] op_sel:[1,0]
	v_pk_mul_f32 v[128:129], v[156:157], v[128:129]
	v_pk_mul_f32 v[130:131], v[158:159], v[130:131]
	v_cvt_pk_bf16_f32 v128, v128, v129
	s_nop 0
	v_cvt_pk_bf16_f32 v129, v130, v131
	v_bfi_b32 v240, v238, v248, v124
	v_bfi_b32 v241, v238, v249, v125
	v_bfi_b32 v242, v238, v250, v126
	v_bfi_b32 v243, v238, v251, v127
	v_lshl_add_u64 v[216:217], v[134:135], 0, v[252:253]
	s_nop 0
	v_mov_b32_dpp v244, v240 quad_perm:[1,0,3,2] row_mask:0xf bank_mask:0xf
	v_mov_b32_dpp v245, v241 quad_perm:[1,0,3,2] row_mask:0xf bank_mask:0xf
	v_mov_b32_dpp v246, v242 quad_perm:[1,0,3,2] row_mask:0xf bank_mask:0xf
	v_mov_b32_dpp v247, v243 quad_perm:[1,0,3,2] row_mask:0xf bank_mask:0xf
	v_bfi_b32 v248, v238, v244, v248
	v_bfi_b32 v249, v238, v245, v249
	v_bfi_b32 v250, v238, v246, v250
	v_bfi_b32 v251, v238, v247, v251
	v_bfi_b32 v244, v238, v124, v244
	v_bfi_b32 v245, v238, v125, v245
	v_bfi_b32 v246, v238, v126, v246
	v_bfi_b32 v247, v238, v127, v247
	global_store_dwordx4 v[216:217], v[248:251], off offset:-2048
	global_store_dwordx4 v[216:217], v[244:247], off offset:2048
	v_mov_b32_e32 v222, v128
	v_mov_b32_e32 v223, v129
	v_lshl_add_u64 v[226:227], v[138:139], 0, v[224:225]
	s_nop 0
	v_permlane32_swap_b32_e32 v220, v222
	v_permlane32_swap_b32_e32 v221, v223
	s_nop 1
	v_permlane16_swap_b32_e32 v220, v222
	v_permlane16_swap_b32_e32 v221, v223
	global_store_dwordx4 v[226:227], v[220:223], off
	global_load_dwordx4 v[124:127], v[168:169], off offset:512
	s_waitcnt vmcnt(0)
	v_pk_fma_f32 v[120:121], v[100:101], v[120:121], v[124:125]
	v_pk_fma_f32 v[122:123], v[102:103], v[122:123], v[126:127]
	v_pk_mul_f32 v[124:125], v[136:137], v[120:121] op_sel:[1,0]
	v_pk_mul_f32 v[126:127], v[136:137], v[122:123] op_sel:[1,0]
	v_pk_mul_f32 v[124:125], v[152:153], v[124:125]
	v_pk_mul_f32 v[126:127], v[154:155], v[126:127]
	v_cvt_pk_bf16_f32 v124, v124, v125
	s_nop 0
	v_cvt_pk_bf16_f32 v125, v126, v127
	v_mov_b32_e32 v248, v120
	v_mov_b32_e32 v249, v121
	v_mov_b32_e32 v250, v122
	v_mov_b32_e32 v251, v123
	v_mov_b32_e32 v220, v124
	v_mov_b32_e32 v221, v125
	global_load_dwordx4 v[120:123], v[168:169], off offset:576
	s_waitcnt vmcnt(0)
; __device__ __forceinline__ unsigned cvt_pk_bf16(float lo, float hi) { unsigned r; asm volatile("v_cvt_pk_bf16_f32 %0, %1, %2" : "=v"(r) : "v"(lo), "v"(hi)); return r; }
;     __device__ __forceinline__ void fused(f32x4 (&acc)[2][2][4][2], const Unit& u, int wr, int wc, int fr, int fq, PG8_LAS unsigned char* lds, int wid, int lane) const {
;     ...
;         for (int ai = 0; ai < 2; ++ai)
; #pragma unroll
;             for (int m = 0; m < 4; ++m) { const int r = ai * HALF + wr * 64 + m * 16 + fr; const f32x2v sr = S[r]; const size_t off = (size_t)(u.pm * BM + r) * 1024 + col0;
; #pragma unroll
;                 for (int bj = 0; bj < 2; ++bj)
; #pragma unroll
;                     for (int n = 0; n < 2; ++n) { const f32x4 bs = *(const f32x4*)(base + off + bj * HALF + n * 16); const f32x4 x1 = bs + acc[ai][bj][m][n] * sr.x * gv[bj][n];
;                         const f32x4 o = x1 * sr.y * g2v[bj][n]; u32x2 w; w.x = cvt_pk_bf16(o[0], o[1]); w.y = cvt_pk_bf16(o[2], o[3]);
;                         if (!dry || x1[0] == 1.2345e38f) { *(f32x4*)(out + off + bj * HALF + n * 16) = x1; *(u32x2*)(xn + off + bj * HALF + n * 16) = w; } }
;                 if (m & 1) asm volatile("" ::: "memory"); }
	v_pk_fma_f32 v[112:113], v[92:93], v[112:113], v[120:121]
	v_pk_fma_f32 v[114:115], v[94:95], v[114:115], v[122:123]
	v_pk_mul_f32 v[120:121], v[136:137], v[112:113] op_sel:[1,0]
	v_pk_mul_f32 v[122:123], v[136:137], v[114:115] op_sel:[1,0]
	v_pk_mul_f32 v[120:121], v[148:149], v[120:121]
	v_pk_mul_f32 v[122:123], v[150:151], v[122:123]
	v_cvt_pk_bf16_f32 v120, v120, v121
	s_nop 0
	v_cvt_pk_bf16_f32 v121, v122, v123
	v_bfi_b32 v240, v238, v248, v112
	v_bfi_b32 v241, v238, v249, v113
	v_bfi_b32 v242, v238, v250, v114
	v_bfi_b32 v243, v238, v251, v115
	v_lshl_add_u64 v[216:217], v[134:135], 0, v[252:253]
	s_nop 0
	v_mov_b32_dpp v244, v240 quad_perm:[1,0,3,2] row_mask:0xf bank_mask:0xf
	v_mov_b32_dpp v245, v241 quad_perm:[1,0,3,2] row_mask:0xf bank_mask:0xf
	v_mov_b32_dpp v246, v242 quad_perm:[1,0,3,2] row_mask:0xf bank_mask:0xf
	v_mov_b32_dpp v247, v243 quad_perm:[1,0,3,2] row_mask:0xf bank_mask:0xf
	v_bfi_b32 v248, v238, v244, v248
	v_bfi_b32 v249, v238, v245, v249
	v_bfi_b32 v250, v238, v246, v250
	v_bfi_b32 v251, v238, v247, v251
	v_bfi_b32 v244, v238, v112, v244
	v_bfi_b32 v245, v238, v113, v245
	v_bfi_b32 v246, v238, v114, v246
	v_bfi_b32 v247, v238, v115, v247
	global_store_dwordx4 v[216:217], v[248:251], off offset:-1536
	global_store_dwordx4 v[216:217], v[244:247], off offset:2560
	v_mov_b32_e32 v222, v120
	v_mov_b32_e32 v223, v121
	v_lshl_add_u64 v[226:227], v[138:139], 0, v[224:225]
	s_nop 0
	v_permlane32_swap_b32_e32 v220, v222
	v_permlane32_swap_b32_e32 v221, v223
	s_nop 1
	v_permlane16_swap_b32_e32 v220, v222
	v_permlane16_swap_b32_e32 v221, v223
	global_store_dwordx4 v[226:227], v[220:223], off offset:256
	ds_read_b64 v[120:121], v33 offset:16640
	v_lshlrev_b64 v[112:113], 10, v[174:175]
	v_lshl_add_u64 v[122:123], v[112:113], 0, v[34:35]
	global_load_dwordx4 v[112:115], v[172:173], off
	s_waitcnt lgkmcnt(0)
	v_pk_mul_f32 v[110:111], v[110:111], v[120:121] op_sel_hi:[1,0]
	v_pk_mul_f32 v[108:109], v[108:109], v[120:121] op_sel_hi:[1,0]
	v_pk_mul_f32 v[96:97], v[96:97], v[120:121] op_sel_hi:[1,0]
	v_pk_mul_f32 v[98:99], v[98:99], v[120:121] op_sel_hi:[1,0]
	v_pk_mul_f32 v[88:89], v[88:89], v[120:121] op_sel_hi:[1,0]
	v_pk_mul_f32 v[90:91], v[90:91], v[120:121] op_sel_hi:[1,0]
	v_pk_mul_f32 v[84:85], v[84:85], v[120:121] op_sel_hi:[1,0]
	v_pk_mul_f32 v[86:87], v[86:87], v[120:121] op_sel_hi:[1,0]
	s_waitcnt vmcnt(0)
	v_pk_fma_f32 v[108:109], v[116:117], v[108:109], v[112:113]
	v_pk_fma_f32 v[110:111], v[118:119], v[110:111], v[114:115]
	v_pk_mul_f32 v[112:113], v[120:121], v[108:109] op_sel:[1,0]
	v_pk_mul_f32 v[114:115], v[120:121], v[110:111] op_sel:[1,0]
	v_pk_mul_f32 v[112:113], v[160:161], v[112:113]
	v_pk_mul_f32 v[114:115], v[162:163], v[114:115]
	v_cvt_pk_bf16_f32 v112, v112, v113
	s_nop 0
	v_cvt_pk_bf16_f32 v113, v114, v115
	v_lshl_add_u64 v[114:115], v[122:123], 2, s[20:21]
	v_lshl_add_u64 v[122:123], v[122:123], 1, s[6:7]
	v_mov_b32_e32 v248, v108
	v_mov_b32_e32 v249, v109
	v_mov_b32_e32 v250, v110
	v_mov_b32_e32 v251, v111
	v_mov_b32_e32 v220, v112
	v_mov_b32_e32 v221, v113
	global_load_dwordx4 v[108:111], v[172:173], off offset:64
	s_waitcnt vmcnt(0)
	v_pk_fma_f32 v[96:97], v[104:105], v[96:97], v[108:109]
	v_pk_fma_f32 v[98:99], v[106:107], v[98:99], v[110:111]
	v_pk_mul_f32 v[108:109], v[120:121], v[96:97] op_sel:[1,0]
	v_pk_mul_f32 v[110:111], v[120:121], v[98:99] op_sel:[1,0]
	v_pk_mul_f32 v[108:109], v[156:157], v[108:109]
	v_pk_mul_f32 v[110:111], v[158:159], v[110:111]
	v_cvt_pk_bf16_f32 v108, v108, v109
	s_nop 0
	v_cvt_pk_bf16_f32 v109, v110, v111
	v_bfi_b32 v240, v238, v248, v96
	v_bfi_b32 v241, v238, v249, v97
	v_bfi_b32 v242, v238, v250, v98
	v_bfi_b32 v243, v238, v251, v99
	v_lshl_add_u64 v[216:217], v[114:115], 0, v[252:253]
	s_nop 0
	v_mov_b32_dpp v244, v240 quad_perm:[1,0,3,2] row_mask:0xf bank_mask:0xf
	v_mov_b32_dpp v245, v241 quad_perm:[1,0,3,2] row_mask:0xf bank_mask:0xf
	v_mov_b32_dpp v246, v242 quad_perm:[1,0,3,2] row_mask:0xf bank_mask:0xf
	v_mov_b32_dpp v247, v243 quad_perm:[1,0,3,2] row_mask:0xf bank_mask:0xf
	v_bfi_b32 v248, v238, v244, v248
	v_bfi_b32 v249, v238, v245, v249
	v_bfi_b32 v250, v238, v246, v250
	v_bfi_b32 v251, v238, v247, v251
	v_bfi_b32 v244, v238, v96, v244
	v_bfi_b32 v245, v238, v97, v245
	v_bfi_b32 v246, v238, v98, v246
	v_bfi_b32 v247, v238, v99, v247
	global_store_dwordx4 v[216:217], v[248:251], off offset:-2048
	global_store_dwordx4 v[216:217], v[244:247], off offset:2048
	v_mov_b32_e32 v222, v108
	v_mov_b32_e32 v223, v109
	v_lshl_add_u64 v[226:227], v[122:123], 0, v[224:225]
	s_nop 0
	v_permlane32_swap_b32_e32 v220, v222
	v_permlane32_swap_b32_e32 v221, v223
	s_nop 1
	v_permlane16_swap_b32_e32 v220, v222
	v_permlane16_swap_b32_e32 v221, v223
	global_store_dwordx4 v[226:227], v[220:223], off
	global_load_dwordx4 v[96:99], v[172:173], off offset:512
	s_waitcnt vmcnt(0)
	v_pk_fma_f32 v[88:89], v[100:101], v[88:89], v[96:97]
	v_pk_fma_f32 v[90:91], v[102:103], v[90:91], v[98:99]
	v_pk_mul_f32 v[96:97], v[120:121], v[88:89] op_sel:[1,0]
	v_pk_mul_f32 v[98:99], v[120:121], v[90:91] op_sel:[1,0]
	v_pk_mul_f32 v[96:97], v[152:153], v[96:97]
	v_pk_mul_f32 v[98:99], v[154:155], v[98:99]
	v_cvt_pk_bf16_f32 v96, v96, v97
	s_nop 0
	v_cvt_pk_bf16_f32 v97, v98, v99
	v_mov_b32_e32 v248, v88
	v_mov_b32_e32 v249, v89
	v_mov_b32_e32 v250, v90
	v_mov_b32_e32 v251, v91
	v_mov_b32_e32 v220, v96
	v_mov_b32_e32 v221, v97
	global_load_dwordx4 v[88:91], v[172:173], off offset:576
	s_waitcnt vmcnt(0)
; __device__ __forceinline__ unsigned cvt_pk_bf16(float lo, float hi) { unsigned r; asm volatile("v_cvt_pk_bf16_f32 %0, %1, %2" : "=v"(r) : "v"(lo), "v"(hi)); return r; }
;     __device__ __forceinline__ void fused(f32x4 (&acc)[2][2][4][2], const Unit& u, int wr, int wc, int fr, int fq, PG8_LAS unsigned char* lds, int wid, int lane) const {
;     ...
;         for (int ai = 0; ai < 2; ++ai)
; #pragma unroll
;             for (int m = 0; m < 4; ++m) { const int r = ai * HALF + wr * 64 + m * 16 + fr; const f32x2v sr = S[r]; const size_t off = (size_t)(u.pm * BM + r) * 1024 + col0;
; #pragma unroll
;                 for (int bj = 0; bj < 2; ++bj)
; #pragma unroll
;                     for (int n = 0; n < 2; ++n) { const f32x4 bs = *(const f32x4*)(base + off + bj * HALF + n * 16); const f32x4 x1 = bs + acc[ai][bj][m][n] * sr.x * gv[bj][n];
;                         const f32x4 o = x1 * sr.y * g2v[bj][n]; u32x2 w; w.x = cvt_pk_bf16(o[0], o[1]); w.y = cvt_pk_bf16(o[2], o[3]);
;                         if (!dry || x1[0] == 1.2345e38f) { *(f32x4*)(out + off + bj * HALF + n * 16) = x1; *(u32x2*)(xn + off + bj * HALF + n * 16) = w; } }
;                 if (m & 1) asm volatile("" ::: "memory"); }
	v_pk_fma_f32 v[84:85], v[92:93], v[84:85], v[88:89]
	v_pk_fma_f32 v[86:87], v[94:95], v[86:87], v[90:91]
	v_pk_mul_f32 v[88:89], v[120:121], v[84:85] op_sel:[1,0]
	v_pk_mul_f32 v[90:91], v[120:121], v[86:87] op_sel:[1,0]
	v_pk_mul_f32 v[88:89], v[148:149], v[88:89]
	v_pk_mul_f32 v[90:91], v[150:151], v[90:91]
	v_cvt_pk_bf16_f32 v88, v88, v89
	s_nop 0
	v_cvt_pk_bf16_f32 v89, v90, v91
	v_bfi_b32 v240, v238, v248, v84
	v_bfi_b32 v241, v238, v249, v85
	v_bfi_b32 v242, v238, v250, v86
	v_bfi_b32 v243, v238, v251, v87
	v_lshl_add_u64 v[216:217], v[114:115], 0, v[252:253]
	s_nop 0
	v_mov_b32_dpp v244, v240 quad_perm:[1,0,3,2] row_mask:0xf bank_mask:0xf
	v_mov_b32_dpp v245, v241 quad_perm:[1,0,3,2] row_mask:0xf bank_mask:0xf
	v_mov_b32_dpp v246, v242 quad_perm:[1,0,3,2] row_mask:0xf bank_mask:0xf
	v_mov_b32_dpp v247, v243 quad_perm:[1,0,3,2] row_mask:0xf bank_mask:0xf
	v_bfi_b32 v248, v238, v244, v248
	v_bfi_b32 v249, v238, v245, v249
	v_bfi_b32 v250, v238, v246, v250
	v_bfi_b32 v251, v238, v247, v251
	v_bfi_b32 v244, v238, v84, v244
	v_bfi_b32 v245, v238, v85, v245
	v_bfi_b32 v246, v238, v86, v246
	v_bfi_b32 v247, v238, v87, v247
	global_store_dwordx4 v[216:217], v[248:251], off offset:-1536
	global_store_dwordx4 v[216:217], v[244:247], off offset:2560
	v_mov_b32_e32 v222, v88
	v_mov_b32_e32 v223, v89
	v_lshl_add_u64 v[226:227], v[122:123], 0, v[224:225]
	s_nop 0
	v_permlane32_swap_b32_e32 v220, v222
	v_permlane32_swap_b32_e32 v221, v223
	s_nop 1
	v_permlane16_swap_b32_e32 v220, v222
	v_permlane16_swap_b32_e32 v221, v223
	global_store_dwordx4 v[226:227], v[220:223], off offset:256
	ds_read_b64 v[88:89], v33 offset:16768
	v_lshlrev_b64 v[84:85], 10, v[178:179]
	v_lshl_add_u64 v[90:91], v[84:85], 0, v[34:35]
	global_load_dwordx4 v[84:87], v[176:177], off
	s_waitcnt lgkmcnt(0)
	v_pk_mul_f32 v[82:83], v[82:83], v[88:89] op_sel_hi:[1,0]
	v_pk_mul_f32 v[80:81], v[80:81], v[88:89] op_sel_hi:[1,0]
	v_pk_mul_f32 v[76:77], v[76:77], v[88:89] op_sel_hi:[1,0]
	v_pk_mul_f32 v[78:79], v[78:79], v[88:89] op_sel_hi:[1,0]
	v_pk_mul_f32 v[72:73], v[72:73], v[88:89] op_sel_hi:[1,0]
	v_pk_mul_f32 v[74:75], v[74:75], v[88:89] op_sel_hi:[1,0]
	v_pk_mul_f32 v[68:69], v[68:69], v[88:89] op_sel_hi:[1,0]
	v_pk_mul_f32 v[70:71], v[70:71], v[88:89] op_sel_hi:[1,0]
	s_waitcnt vmcnt(0)
	v_pk_fma_f32 v[80:81], v[116:117], v[80:81], v[84:85]
	v_pk_fma_f32 v[82:83], v[118:119], v[82:83], v[86:87]
	v_pk_mul_f32 v[84:85], v[88:89], v[80:81] op_sel:[1,0]
	v_pk_mul_f32 v[86:87], v[88:89], v[82:83] op_sel:[1,0]
	v_pk_mul_f32 v[84:85], v[160:161], v[84:85]
	v_pk_mul_f32 v[86:87], v[162:163], v[86:87]
	v_cvt_pk_bf16_f32 v84, v84, v85
	s_nop 0
	v_cvt_pk_bf16_f32 v85, v86, v87
	v_lshl_add_u64 v[86:87], v[90:91], 2, s[20:21]
	v_lshl_add_u64 v[90:91], v[90:91], 1, s[6:7]
	v_mov_b32_e32 v248, v80
	v_mov_b32_e32 v249, v81
	v_mov_b32_e32 v250, v82
	v_mov_b32_e32 v251, v83
	v_mov_b32_e32 v220, v84
	v_mov_b32_e32 v221, v85
	global_load_dwordx4 v[80:83], v[176:177], off offset:64
	s_waitcnt vmcnt(0)
	v_pk_fma_f32 v[76:77], v[104:105], v[76:77], v[80:81]
	v_pk_fma_f32 v[78:79], v[106:107], v[78:79], v[82:83]
	v_pk_mul_f32 v[80:81], v[88:89], v[76:77] op_sel:[1,0]
	v_pk_mul_f32 v[82:83], v[88:89], v[78:79] op_sel:[1,0]
	v_pk_mul_f32 v[80:81], v[156:157], v[80:81]
	v_pk_mul_f32 v[82:83], v[158:159], v[82:83]
	v_cvt_pk_bf16_f32 v80, v80, v81
	s_nop 0
	v_cvt_pk_bf16_f32 v81, v82, v83
	v_bfi_b32 v240, v238, v248, v76
	v_bfi_b32 v241, v238, v249, v77
	v_bfi_b32 v242, v238, v250, v78
	v_bfi_b32 v243, v238, v251, v79
	v_lshl_add_u64 v[216:217], v[86:87], 0, v[252:253]
	s_nop 0
	v_mov_b32_dpp v244, v240 quad_perm:[1,0,3,2] row_mask:0xf bank_mask:0xf
	v_mov_b32_dpp v245, v241 quad_perm:[1,0,3,2] row_mask:0xf bank_mask:0xf
	v_mov_b32_dpp v246, v242 quad_perm:[1,0,3,2] row_mask:0xf bank_mask:0xf
	v_mov_b32_dpp v247, v243 quad_perm:[1,0,3,2] row_mask:0xf bank_mask:0xf
	v_bfi_b32 v248, v238, v244, v248
	v_bfi_b32 v249, v238, v245, v249
	v_bfi_b32 v250, v238, v246, v250
	v_bfi_b32 v251, v238, v247, v251
	v_bfi_b32 v244, v238, v76, v244
	v_bfi_b32 v245, v238, v77, v245
	v_bfi_b32 v246, v238, v78, v246
	v_bfi_b32 v247, v238, v79, v247
	global_store_dwordx4 v[216:217], v[248:251], off offset:-2048
	global_store_dwordx4 v[216:217], v[244:247], off offset:2048
	v_mov_b32_e32 v222, v80
	v_mov_b32_e32 v223, v81
	v_lshl_add_u64 v[226:227], v[90:91], 0, v[224:225]
	s_nop 0
	v_permlane32_swap_b32_e32 v220, v222
	v_permlane32_swap_b32_e32 v221, v223
	s_nop 1
	v_permlane16_swap_b32_e32 v220, v222
	v_permlane16_swap_b32_e32 v221, v223
	global_store_dwordx4 v[226:227], v[220:223], off
	global_load_dwordx4 v[76:79], v[176:177], off offset:512
	s_waitcnt vmcnt(0)
	v_pk_fma_f32 v[72:73], v[100:101], v[72:73], v[76:77]
	v_pk_fma_f32 v[74:75], v[102:103], v[74:75], v[78:79]
	v_pk_mul_f32 v[76:77], v[88:89], v[72:73] op_sel:[1,0]
	v_pk_mul_f32 v[78:79], v[88:89], v[74:75] op_sel:[1,0]
	v_pk_mul_f32 v[76:77], v[152:153], v[76:77]
	v_pk_mul_f32 v[78:79], v[154:155], v[78:79]
	v_cvt_pk_bf16_f32 v76, v76, v77
	s_nop 0
	v_cvt_pk_bf16_f32 v77, v78, v79
	v_mov_b32_e32 v248, v72
	v_mov_b32_e32 v249, v73
	v_mov_b32_e32 v250, v74
	v_mov_b32_e32 v251, v75
	v_mov_b32_e32 v220, v76
	v_mov_b32_e32 v221, v77
	global_load_dwordx4 v[72:75], v[176:177], off offset:576
	s_waitcnt vmcnt(0)
; __device__ __forceinline__ unsigned cvt_pk_bf16(float lo, float hi) { unsigned r; asm volatile("v_cvt_pk_bf16_f32 %0, %1, %2" : "=v"(r) : "v"(lo), "v"(hi)); return r; }
;     __device__ __forceinline__ void fused(f32x4 (&acc)[2][2][4][2], const Unit& u, int wr, int wc, int fr, int fq, PG8_LAS unsigned char* lds, int wid, int lane) const {
;     ...
;         for (int ai = 0; ai < 2; ++ai)
; #pragma unroll
;             for (int m = 0; m < 4; ++m) { const int r = ai * HALF + wr * 64 + m * 16 + fr; const f32x2v sr = S[r]; const size_t off = (size_t)(u.pm * BM + r) * 1024 + col0;
; #pragma unroll
;                 for (int bj = 0; bj < 2; ++bj)
; #pragma unroll
;                     for (int n = 0; n < 2; ++n) { const f32x4 bs = *(const f32x4*)(base + off + bj * HALF + n * 16); const f32x4 x1 = bs + acc[ai][bj][m][n] * sr.x * gv[bj][n];
;                         const f32x4 o = x1 * sr.y * g2v[bj][n]; u32x2 w; w.x = cvt_pk_bf16(o[0], o[1]); w.y = cvt_pk_bf16(o[2], o[3]);
;                         if (!dry || x1[0] == 1.2345e38f) { *(f32x4*)(out + off + bj * HALF + n * 16) = x1; *(u32x2*)(xn + off + bj * HALF + n * 16) = w; } }
;                 if (m & 1) asm volatile("" ::: "memory"); }
	v_pk_fma_f32 v[68:69], v[92:93], v[68:69], v[72:73]
	v_pk_fma_f32 v[70:71], v[94:95], v[70:71], v[74:75]
	v_pk_mul_f32 v[72:73], v[88:89], v[68:69] op_sel:[1,0]
	v_pk_mul_f32 v[74:75], v[88:89], v[70:71] op_sel:[1,0]
	v_pk_mul_f32 v[72:73], v[148:149], v[72:73]
	v_pk_mul_f32 v[74:75], v[150:151], v[74:75]
	v_cvt_pk_bf16_f32 v72, v72, v73
	s_nop 0
	v_cvt_pk_bf16_f32 v73, v74, v75
	v_bfi_b32 v240, v238, v248, v68
	v_bfi_b32 v241, v238, v249, v69
	v_bfi_b32 v242, v238, v250, v70
	v_bfi_b32 v243, v238, v251, v71
	v_lshl_add_u64 v[216:217], v[86:87], 0, v[252:253]
	s_nop 0
	v_mov_b32_dpp v244, v240 quad_perm:[1,0,3,2] row_mask:0xf bank_mask:0xf
	v_mov_b32_dpp v245, v241 quad_perm:[1,0,3,2] row_mask:0xf bank_mask:0xf
	v_mov_b32_dpp v246, v242 quad_perm:[1,0,3,2] row_mask:0xf bank_mask:0xf
	v_mov_b32_dpp v247, v243 quad_perm:[1,0,3,2] row_mask:0xf bank_mask:0xf
	v_bfi_b32 v248, v238, v244, v248
	v_bfi_b32 v249, v238, v245, v249
	v_bfi_b32 v250, v238, v246, v250
	v_bfi_b32 v251, v238, v247, v251
	v_bfi_b32 v244, v238, v68, v244
	v_bfi_b32 v245, v238, v69, v245
	v_bfi_b32 v246, v238, v70, v246
	v_bfi_b32 v247, v238, v71, v247
	global_store_dwordx4 v[216:217], v[248:251], off offset:-1536
	global_store_dwordx4 v[216:217], v[244:247], off offset:2560
	v_mov_b32_e32 v222, v72
	v_mov_b32_e32 v223, v73
	v_lshl_add_u64 v[226:227], v[90:91], 0, v[224:225]
	s_nop 0
	v_permlane32_swap_b32_e32 v220, v222
	v_permlane32_swap_b32_e32 v221, v223
	s_nop 1
	v_permlane16_swap_b32_e32 v220, v222
	v_permlane16_swap_b32_e32 v221, v223
	global_store_dwordx4 v[226:227], v[220:223], off offset:256
	ds_read_b64 v[72:73], v33 offset:17408
	v_lshlrev_b64 v[68:69], 10, v[182:183]
	v_lshl_add_u64 v[74:75], v[68:69], 0, v[34:35]
	global_load_dwordx4 v[68:71], v[180:181], off
	s_waitcnt lgkmcnt(0)
	v_pk_mul_f32 v[66:67], v[66:67], v[72:73] op_sel_hi:[1,0]
	v_pk_mul_f32 v[64:65], v[64:65], v[72:73] op_sel_hi:[1,0]
	v_pk_mul_f32 v[60:61], v[60:61], v[72:73] op_sel_hi:[1,0]
	v_pk_mul_f32 v[62:63], v[62:63], v[72:73] op_sel_hi:[1,0]
	v_pk_mul_f32 v[56:57], v[56:57], v[72:73] op_sel_hi:[1,0]
	v_pk_mul_f32 v[58:59], v[58:59], v[72:73] op_sel_hi:[1,0]
	v_pk_mul_f32 v[52:53], v[52:53], v[72:73] op_sel_hi:[1,0]
	v_pk_mul_f32 v[54:55], v[54:55], v[72:73] op_sel_hi:[1,0]
	s_waitcnt vmcnt(0)
	v_pk_fma_f32 v[64:65], v[116:117], v[64:65], v[68:69]
	v_pk_fma_f32 v[66:67], v[118:119], v[66:67], v[70:71]
	v_pk_mul_f32 v[68:69], v[72:73], v[64:65] op_sel:[1,0]
	v_pk_mul_f32 v[70:71], v[72:73], v[66:67] op_sel:[1,0]
	v_pk_mul_f32 v[68:69], v[160:161], v[68:69]
	v_pk_mul_f32 v[70:71], v[162:163], v[70:71]
	v_cvt_pk_bf16_f32 v68, v68, v69
	s_nop 0
	v_cvt_pk_bf16_f32 v69, v70, v71
	v_lshl_add_u64 v[70:71], v[74:75], 2, s[20:21]
	v_lshl_add_u64 v[74:75], v[74:75], 1, s[6:7]
	v_mov_b32_e32 v248, v64
	v_mov_b32_e32 v249, v65
	v_mov_b32_e32 v250, v66
	v_mov_b32_e32 v251, v67
	v_mov_b32_e32 v220, v68
	v_mov_b32_e32 v221, v69
	global_load_dwordx4 v[64:67], v[180:181], off offset:64
	s_waitcnt vmcnt(0)
	v_pk_fma_f32 v[60:61], v[104:105], v[60:61], v[64:65]
	v_pk_fma_f32 v[62:63], v[106:107], v[62:63], v[66:67]
	v_pk_mul_f32 v[64:65], v[72:73], v[60:61] op_sel:[1,0]
	v_pk_mul_f32 v[66:67], v[72:73], v[62:63] op_sel:[1,0]
	v_pk_mul_f32 v[64:65], v[156:157], v[64:65]
	v_pk_mul_f32 v[66:67], v[158:159], v[66:67]
	v_cvt_pk_bf16_f32 v64, v64, v65
	s_nop 0
	v_cvt_pk_bf16_f32 v65, v66, v67
	v_bfi_b32 v240, v238, v248, v60
	v_bfi_b32 v241, v238, v249, v61
	v_bfi_b32 v242, v238, v250, v62
	v_bfi_b32 v243, v238, v251, v63
	v_lshl_add_u64 v[216:217], v[70:71], 0, v[252:253]
	s_nop 0
	v_mov_b32_dpp v244, v240 quad_perm:[1,0,3,2] row_mask:0xf bank_mask:0xf
	v_mov_b32_dpp v245, v241 quad_perm:[1,0,3,2] row_mask:0xf bank_mask:0xf
	v_mov_b32_dpp v246, v242 quad_perm:[1,0,3,2] row_mask:0xf bank_mask:0xf
	v_mov_b32_dpp v247, v243 quad_perm:[1,0,3,2] row_mask:0xf bank_mask:0xf
	v_bfi_b32 v248, v238, v244, v248
	v_bfi_b32 v249, v238, v245, v249
	v_bfi_b32 v250, v238, v246, v250
	v_bfi_b32 v251, v238, v247, v251
	v_bfi_b32 v244, v238, v60, v244
	v_bfi_b32 v245, v238, v61, v245
	v_bfi_b32 v246, v238, v62, v246
	v_bfi_b32 v247, v238, v63, v247
	global_store_dwordx4 v[216:217], v[248:251], off offset:-2048
	global_store_dwordx4 v[216:217], v[244:247], off offset:2048
	v_mov_b32_e32 v222, v64
	v_mov_b32_e32 v223, v65
	v_lshl_add_u64 v[226:227], v[74:75], 0, v[224:225]
	s_nop 0
	v_permlane32_swap_b32_e32 v220, v222
	v_permlane32_swap_b32_e32 v221, v223
	s_nop 1
	v_permlane16_swap_b32_e32 v220, v222
	v_permlane16_swap_b32_e32 v221, v223
	global_store_dwordx4 v[226:227], v[220:223], off
	global_load_dwordx4 v[60:63], v[180:181], off offset:512
	s_waitcnt vmcnt(0)
	v_pk_fma_f32 v[56:57], v[100:101], v[56:57], v[60:61]
	v_pk_fma_f32 v[58:59], v[102:103], v[58:59], v[62:63]
	v_pk_mul_f32 v[60:61], v[72:73], v[56:57] op_sel:[1,0]
	v_pk_mul_f32 v[62:63], v[72:73], v[58:59] op_sel:[1,0]
	v_pk_mul_f32 v[60:61], v[152:153], v[60:61]
	v_pk_mul_f32 v[62:63], v[154:155], v[62:63]
	v_cvt_pk_bf16_f32 v60, v60, v61
	s_nop 0
	v_cvt_pk_bf16_f32 v61, v62, v63
	v_mov_b32_e32 v248, v56
	v_mov_b32_e32 v249, v57
	v_mov_b32_e32 v250, v58
	v_mov_b32_e32 v251, v59
	v_mov_b32_e32 v220, v60
	v_mov_b32_e32 v221, v61
	global_load_dwordx4 v[56:59], v[180:181], off offset:576
	s_waitcnt vmcnt(0)
; __device__ __forceinline__ unsigned cvt_pk_bf16(float lo, float hi) { unsigned r; asm volatile("v_cvt_pk_bf16_f32 %0, %1, %2" : "=v"(r) : "v"(lo), "v"(hi)); return r; }
;     __device__ __forceinline__ void fused(f32x4 (&acc)[2][2][4][2], const Unit& u, int wr, int wc, int fr, int fq, PG8_LAS unsigned char* lds, int wid, int lane) const {
;     ...
;         for (int ai = 0; ai < 2; ++ai)
; #pragma unroll
;             for (int m = 0; m < 4; ++m) { const int r = ai * HALF + wr * 64 + m * 16 + fr; const f32x2v sr = S[r]; const size_t off = (size_t)(u.pm * BM + r) * 1024 + col0;
; #pragma unroll
;                 for (int bj = 0; bj < 2; ++bj)
; #pragma unroll
;                     for (int n = 0; n < 2; ++n) { const f32x4 bs = *(const f32x4*)(base + off + bj * HALF + n * 16); const f32x4 x1 = bs + acc[ai][bj][m][n] * sr.x * gv[bj][n];
;                         const f32x4 o = x1 * sr.y * g2v[bj][n]; u32x2 w; w.x = cvt_pk_bf16(o[0], o[1]); w.y = cvt_pk_bf16(o[2], o[3]);
;                         if (!dry || x1[0] == 1.2345e38f) { *(f32x4*)(out + off + bj * HALF + n * 16) = x1; *(u32x2*)(xn + off + bj * HALF + n * 16) = w; } }
;                 if (m & 1) asm volatile("" ::: "memory"); }
	v_pk_fma_f32 v[52:53], v[92:93], v[52:53], v[56:57]
	v_pk_fma_f32 v[54:55], v[94:95], v[54:55], v[58:59]
	v_pk_mul_f32 v[56:57], v[72:73], v[52:53] op_sel:[1,0]
	v_pk_mul_f32 v[58:59], v[72:73], v[54:55] op_sel:[1,0]
	v_pk_mul_f32 v[56:57], v[148:149], v[56:57]
	v_pk_mul_f32 v[58:59], v[150:151], v[58:59]
	v_cvt_pk_bf16_f32 v56, v56, v57
	s_nop 0
	v_cvt_pk_bf16_f32 v57, v58, v59
	v_bfi_b32 v240, v238, v248, v52
	v_bfi_b32 v241, v238, v249, v53
	v_bfi_b32 v242, v238, v250, v54
	v_bfi_b32 v243, v238, v251, v55
	v_lshl_add_u64 v[216:217], v[70:71], 0, v[252:253]
	s_nop 0
	v_mov_b32_dpp v244, v240 quad_perm:[1,0,3,2] row_mask:0xf bank_mask:0xf
	v_mov_b32_dpp v245, v241 quad_perm:[1,0,3,2] row_mask:0xf bank_mask:0xf
	v_mov_b32_dpp v246, v242 quad_perm:[1,0,3,2] row_mask:0xf bank_mask:0xf
	v_mov_b32_dpp v247, v243 quad_perm:[1,0,3,2] row_mask:0xf bank_mask:0xf
	v_bfi_b32 v248, v238, v244, v248
	v_bfi_b32 v249, v238, v245, v249
	v_bfi_b32 v250, v238, v246, v250
	v_bfi_b32 v251, v238, v247, v251
	v_bfi_b32 v244, v238, v52, v244
	v_bfi_b32 v245, v238, v53, v245
	v_bfi_b32 v246, v238, v54, v246
	v_bfi_b32 v247, v238, v55, v247
	global_store_dwordx4 v[216:217], v[248:251], off offset:-1536
	global_store_dwordx4 v[216:217], v[244:247], off offset:2560
	v_mov_b32_e32 v222, v56
	v_mov_b32_e32 v223, v57
	v_lshl_add_u64 v[226:227], v[74:75], 0, v[224:225]
	s_nop 0
	v_permlane32_swap_b32_e32 v220, v222
	v_permlane32_swap_b32_e32 v221, v223
	s_nop 1
	v_permlane16_swap_b32_e32 v220, v222
	v_permlane16_swap_b32_e32 v221, v223
	global_store_dwordx4 v[226:227], v[220:223], off offset:256
	ds_read_b64 v[56:57], v33 offset:17536
	v_lshlrev_b64 v[52:53], 10, v[186:187]
	v_lshl_add_u64 v[58:59], v[52:53], 0, v[34:35]
	global_load_dwordx4 v[52:55], v[184:185], off
	s_waitcnt lgkmcnt(0)
	v_pk_mul_f32 v[50:51], v[50:51], v[56:57] op_sel_hi:[1,0]
	v_pk_mul_f32 v[48:49], v[48:49], v[56:57] op_sel_hi:[1,0]
	v_pk_mul_f32 v[44:45], v[44:45], v[56:57] op_sel_hi:[1,0]
	v_pk_mul_f32 v[46:47], v[46:47], v[56:57] op_sel_hi:[1,0]
	v_pk_mul_f32 v[40:41], v[40:41], v[56:57] op_sel_hi:[1,0]
	v_pk_mul_f32 v[42:43], v[42:43], v[56:57] op_sel_hi:[1,0]
	v_pk_mul_f32 v[36:37], v[36:37], v[56:57] op_sel_hi:[1,0]
	v_pk_mul_f32 v[38:39], v[38:39], v[56:57] op_sel_hi:[1,0]
	s_waitcnt vmcnt(0)
	v_pk_fma_f32 v[48:49], v[116:117], v[48:49], v[52:53]
	v_pk_fma_f32 v[50:51], v[118:119], v[50:51], v[54:55]
	v_pk_mul_f32 v[52:53], v[56:57], v[48:49] op_sel:[1,0]
	v_pk_mul_f32 v[54:55], v[56:57], v[50:51] op_sel:[1,0]
	v_pk_mul_f32 v[52:53], v[160:161], v[52:53]
	v_pk_mul_f32 v[54:55], v[162:163], v[54:55]
	v_cvt_pk_bf16_f32 v52, v52, v53
	s_nop 0
	v_cvt_pk_bf16_f32 v53, v54, v55
	v_lshl_add_u64 v[54:55], v[58:59], 2, s[20:21]
	v_lshl_add_u64 v[58:59], v[58:59], 1, s[6:7]
	v_mov_b32_e32 v248, v48
	v_mov_b32_e32 v249, v49
	v_mov_b32_e32 v250, v50
	v_mov_b32_e32 v251, v51
	v_mov_b32_e32 v220, v52
	v_mov_b32_e32 v221, v53
	global_load_dwordx4 v[48:51], v[184:185], off offset:64
	s_waitcnt vmcnt(0)
	v_pk_fma_f32 v[44:45], v[104:105], v[44:45], v[48:49]
	v_pk_fma_f32 v[46:47], v[106:107], v[46:47], v[50:51]
	v_pk_mul_f32 v[48:49], v[56:57], v[44:45] op_sel:[1,0]
	v_pk_mul_f32 v[50:51], v[56:57], v[46:47] op_sel:[1,0]
	v_pk_mul_f32 v[48:49], v[156:157], v[48:49]
	v_pk_mul_f32 v[50:51], v[158:159], v[50:51]
	v_cvt_pk_bf16_f32 v48, v48, v49
	s_nop 0
	v_cvt_pk_bf16_f32 v49, v50, v51
	v_bfi_b32 v240, v238, v248, v44
	v_bfi_b32 v241, v238, v249, v45
	v_bfi_b32 v242, v238, v250, v46
	v_bfi_b32 v243, v238, v251, v47
	v_lshl_add_u64 v[216:217], v[54:55], 0, v[252:253]
	s_nop 0
	v_mov_b32_dpp v244, v240 quad_perm:[1,0,3,2] row_mask:0xf bank_mask:0xf
	v_mov_b32_dpp v245, v241 quad_perm:[1,0,3,2] row_mask:0xf bank_mask:0xf
	v_mov_b32_dpp v246, v242 quad_perm:[1,0,3,2] row_mask:0xf bank_mask:0xf
	v_mov_b32_dpp v247, v243 quad_perm:[1,0,3,2] row_mask:0xf bank_mask:0xf
	v_bfi_b32 v248, v238, v244, v248
	v_bfi_b32 v249, v238, v245, v249
	v_bfi_b32 v250, v238, v246, v250
	v_bfi_b32 v251, v238, v247, v251
	v_bfi_b32 v244, v238, v44, v244
	v_bfi_b32 v245, v238, v45, v245
	v_bfi_b32 v246, v238, v46, v246
	v_bfi_b32 v247, v238, v47, v247
	global_store_dwordx4 v[216:217], v[248:251], off offset:-2048
	global_store_dwordx4 v[216:217], v[244:247], off offset:2048
	v_mov_b32_e32 v222, v48
	v_mov_b32_e32 v223, v49
	v_lshl_add_u64 v[226:227], v[58:59], 0, v[224:225]
	s_nop 0
	v_permlane32_swap_b32_e32 v220, v222
	v_permlane32_swap_b32_e32 v221, v223
	s_nop 1
	v_permlane16_swap_b32_e32 v220, v222
	v_permlane16_swap_b32_e32 v221, v223
	global_store_dwordx4 v[226:227], v[220:223], off
	global_load_dwordx4 v[44:47], v[184:185], off offset:512
	s_waitcnt vmcnt(0)
	v_pk_fma_f32 v[40:41], v[100:101], v[40:41], v[44:45]
	v_pk_fma_f32 v[42:43], v[102:103], v[42:43], v[46:47]
	v_pk_mul_f32 v[44:45], v[56:57], v[40:41] op_sel:[1,0]
	v_pk_mul_f32 v[46:47], v[56:57], v[42:43] op_sel:[1,0]
	v_pk_mul_f32 v[44:45], v[152:153], v[44:45]
	v_pk_mul_f32 v[46:47], v[154:155], v[46:47]
	v_cvt_pk_bf16_f32 v44, v44, v45
	s_nop 0
	v_cvt_pk_bf16_f32 v45, v46, v47
	v_mov_b32_e32 v248, v40
	v_mov_b32_e32 v249, v41
	v_mov_b32_e32 v250, v42
	v_mov_b32_e32 v251, v43
	v_mov_b32_e32 v220, v44
	v_mov_b32_e32 v221, v45
	global_load_dwordx4 v[40:43], v[184:185], off offset:576
	s_waitcnt vmcnt(0)
; __device__ __forceinline__ unsigned cvt_pk_bf16(float lo, float hi) { unsigned r; asm volatile("v_cvt_pk_bf16_f32 %0, %1, %2" : "=v"(r) : "v"(lo), "v"(hi)); return r; }
;     __device__ __forceinline__ void fused(f32x4 (&acc)[2][2][4][2], const Unit& u, int wr, int wc, int fr, int fq, PG8_LAS unsigned char* lds, int wid, int lane) const {
;     ...
;         for (int ai = 0; ai < 2; ++ai)
; #pragma unroll
;             for (int m = 0; m < 4; ++m) { const int r = ai * HALF + wr * 64 + m * 16 + fr; const f32x2v sr = S[r]; const size_t off = (size_t)(u.pm * BM + r) * 1024 + col0;
; #pragma unroll
;                 for (int bj = 0; bj < 2; ++bj)
; #pragma unroll
;                     for (int n = 0; n < 2; ++n) { const f32x4 bs = *(const f32x4*)(base + off + bj * HALF + n * 16); const f32x4 x1 = bs + acc[ai][bj][m][n] * sr.x * gv[bj][n];
;                         const f32x4 o = x1 * sr.y * g2v[bj][n]; u32x2 w; w.x = cvt_pk_bf16(o[0], o[1]); w.y = cvt_pk_bf16(o[2], o[3]);
;                         if (!dry || x1[0] == 1.2345e38f) { *(f32x4*)(out + off + bj * HALF + n * 16) = x1; *(u32x2*)(xn + off + bj * HALF + n * 16) = w; } }
;                 if (m & 1) asm volatile("" ::: "memory"); }
	v_pk_fma_f32 v[36:37], v[92:93], v[36:37], v[40:41]
	v_pk_fma_f32 v[38:39], v[94:95], v[38:39], v[42:43]
	v_pk_mul_f32 v[40:41], v[56:57], v[36:37] op_sel:[1,0]
	v_pk_mul_f32 v[42:43], v[56:57], v[38:39] op_sel:[1,0]
	v_pk_mul_f32 v[40:41], v[148:149], v[40:41]
	v_pk_mul_f32 v[42:43], v[150:151], v[42:43]
	v_cvt_pk_bf16_f32 v40, v40, v41
	s_nop 0
	v_cvt_pk_bf16_f32 v41, v42, v43
	v_bfi_b32 v240, v238, v248, v36
	v_bfi_b32 v241, v238, v249, v37
	v_bfi_b32 v242, v238, v250, v38
	v_bfi_b32 v243, v238, v251, v39
	v_lshl_add_u64 v[216:217], v[54:55], 0, v[252:253]
	s_nop 0
	v_mov_b32_dpp v244, v240 quad_perm:[1,0,3,2] row_mask:0xf bank_mask:0xf
	v_mov_b32_dpp v245, v241 quad_perm:[1,0,3,2] row_mask:0xf bank_mask:0xf
	v_mov_b32_dpp v246, v242 quad_perm:[1,0,3,2] row_mask:0xf bank_mask:0xf
	v_mov_b32_dpp v247, v243 quad_perm:[1,0,3,2] row_mask:0xf bank_mask:0xf
	v_bfi_b32 v248, v238, v244, v248
	v_bfi_b32 v249, v238, v245, v249
	v_bfi_b32 v250, v238, v246, v250
	v_bfi_b32 v251, v238, v247, v251
	v_bfi_b32 v244, v238, v36, v244
	v_bfi_b32 v245, v238, v37, v245
	v_bfi_b32 v246, v238, v38, v246
	v_bfi_b32 v247, v238, v39, v247
	global_store_dwordx4 v[216:217], v[248:251], off offset:-1536
	global_store_dwordx4 v[216:217], v[244:247], off offset:2560
	v_mov_b32_e32 v222, v40
	v_mov_b32_e32 v223, v41
	v_lshl_add_u64 v[226:227], v[58:59], 0, v[224:225]
	s_nop 0
	v_permlane32_swap_b32_e32 v220, v222
	v_permlane32_swap_b32_e32 v221, v223
	s_nop 1
	v_permlane16_swap_b32_e32 v220, v222
	v_permlane16_swap_b32_e32 v221, v223
	global_store_dwordx4 v[226:227], v[220:223], off offset:256
	ds_read_b64 v[40:41], v33 offset:17664
	v_lshlrev_b64 v[36:37], 10, v[190:191]
	v_lshl_add_u64 v[42:43], v[36:37], 0, v[34:35]
	global_load_dwordx4 v[36:39], v[188:189], off
	s_waitcnt lgkmcnt(0)
	v_pk_mul_f32 v[30:31], v[30:31], v[40:41] op_sel_hi:[1,0]
	v_pk_mul_f32 v[28:29], v[28:29], v[40:41] op_sel_hi:[1,0]
	v_pk_mul_f32 v[24:25], v[24:25], v[40:41] op_sel_hi:[1,0]
	v_pk_mul_f32 v[26:27], v[26:27], v[40:41] op_sel_hi:[1,0]
	v_pk_mul_f32 v[20:21], v[20:21], v[40:41] op_sel_hi:[1,0]
	v_pk_mul_f32 v[22:23], v[22:23], v[40:41] op_sel_hi:[1,0]
	v_pk_mul_f32 v[16:17], v[16:17], v[40:41] op_sel_hi:[1,0]
	v_pk_mul_f32 v[18:19], v[18:19], v[40:41] op_sel_hi:[1,0]
	s_waitcnt vmcnt(0)
	v_pk_fma_f32 v[28:29], v[116:117], v[28:29], v[36:37]
	v_pk_fma_f32 v[30:31], v[118:119], v[30:31], v[38:39]
	v_pk_mul_f32 v[36:37], v[40:41], v[28:29] op_sel:[1,0]
	v_pk_mul_f32 v[38:39], v[40:41], v[30:31] op_sel:[1,0]
	v_pk_mul_f32 v[36:37], v[160:161], v[36:37]
	v_pk_mul_f32 v[38:39], v[162:163], v[38:39]
	v_cvt_pk_bf16_f32 v36, v36, v37
	s_nop 0
	v_cvt_pk_bf16_f32 v37, v38, v39
	v_lshl_add_u64 v[38:39], v[42:43], 2, s[20:21]
	v_lshl_add_u64 v[42:43], v[42:43], 1, s[6:7]
	v_mov_b32_e32 v248, v28
	v_mov_b32_e32 v249, v29
	v_mov_b32_e32 v250, v30
	v_mov_b32_e32 v251, v31
	v_mov_b32_e32 v220, v36
	v_mov_b32_e32 v221, v37
	global_load_dwordx4 v[28:31], v[188:189], off offset:64
	s_waitcnt vmcnt(0)
	v_pk_fma_f32 v[24:25], v[104:105], v[24:25], v[28:29]
	v_pk_fma_f32 v[26:27], v[106:107], v[26:27], v[30:31]
	v_pk_mul_f32 v[28:29], v[40:41], v[24:25] op_sel:[1,0]
	v_pk_mul_f32 v[30:31], v[40:41], v[26:27] op_sel:[1,0]
	v_pk_mul_f32 v[28:29], v[156:157], v[28:29]
	v_pk_mul_f32 v[30:31], v[158:159], v[30:31]
	v_cvt_pk_bf16_f32 v28, v28, v29
	s_nop 0
	v_cvt_pk_bf16_f32 v29, v30, v31
	v_bfi_b32 v240, v238, v248, v24
	v_bfi_b32 v241, v238, v249, v25
	v_bfi_b32 v242, v238, v250, v26
	v_bfi_b32 v243, v238, v251, v27
	v_lshl_add_u64 v[216:217], v[38:39], 0, v[252:253]
	s_nop 0
	v_mov_b32_dpp v244, v240 quad_perm:[1,0,3,2] row_mask:0xf bank_mask:0xf
	v_mov_b32_dpp v245, v241 quad_perm:[1,0,3,2] row_mask:0xf bank_mask:0xf
	v_mov_b32_dpp v246, v242 quad_perm:[1,0,3,2] row_mask:0xf bank_mask:0xf
	v_mov_b32_dpp v247, v243 quad_perm:[1,0,3,2] row_mask:0xf bank_mask:0xf
	v_bfi_b32 v248, v238, v244, v248
	v_bfi_b32 v249, v238, v245, v249
	v_bfi_b32 v250, v238, v246, v250
	v_bfi_b32 v251, v238, v247, v251
	v_bfi_b32 v244, v238, v24, v244
	v_bfi_b32 v245, v238, v25, v245
	v_bfi_b32 v246, v238, v26, v246
	v_bfi_b32 v247, v238, v27, v247
	global_store_dwordx4 v[216:217], v[248:251], off offset:-2048
	global_store_dwordx4 v[216:217], v[244:247], off offset:2048
	v_mov_b32_e32 v222, v28
	v_mov_b32_e32 v223, v29
	v_lshl_add_u64 v[226:227], v[42:43], 0, v[224:225]
	s_nop 0
	v_permlane32_swap_b32_e32 v220, v222
	v_permlane32_swap_b32_e32 v221, v223
	s_nop 1
	v_permlane16_swap_b32_e32 v220, v222
	v_permlane16_swap_b32_e32 v221, v223
	global_store_dwordx4 v[226:227], v[220:223], off
	global_load_dwordx4 v[24:27], v[188:189], off offset:512
	s_waitcnt vmcnt(0)
	v_pk_fma_f32 v[20:21], v[100:101], v[20:21], v[24:25]
	v_pk_fma_f32 v[22:23], v[102:103], v[22:23], v[26:27]
	v_pk_mul_f32 v[24:25], v[40:41], v[20:21] op_sel:[1,0]
	v_pk_mul_f32 v[26:27], v[40:41], v[22:23] op_sel:[1,0]
	v_pk_mul_f32 v[24:25], v[152:153], v[24:25]
	v_pk_mul_f32 v[26:27], v[154:155], v[26:27]
	v_cvt_pk_bf16_f32 v24, v24, v25
	s_nop 0
	v_cvt_pk_bf16_f32 v25, v26, v27
	v_mov_b32_e32 v248, v20
	v_mov_b32_e32 v249, v21
	v_mov_b32_e32 v250, v22
	v_mov_b32_e32 v251, v23
	v_mov_b32_e32 v220, v24
	v_mov_b32_e32 v221, v25
	global_load_dwordx4 v[20:23], v[188:189], off offset:576
	s_waitcnt vmcnt(0)
; __device__ __forceinline__ unsigned cvt_pk_bf16(float lo, float hi) { unsigned r; asm volatile("v_cvt_pk_bf16_f32 %0, %1, %2" : "=v"(r) : "v"(lo), "v"(hi)); return r; }
;     __device__ __forceinline__ void fused(f32x4 (&acc)[2][2][4][2], const Unit& u, int wr, int wc, int fr, int fq, PG8_LAS unsigned char* lds, int wid, int lane) const {
;     ...
;         for (int ai = 0; ai < 2; ++ai)
; #pragma unroll
;             for (int m = 0; m < 4; ++m) { const int r = ai * HALF + wr * 64 + m * 16 + fr; const f32x2v sr = S[r]; const size_t off = (size_t)(u.pm * BM + r) * 1024 + col0;
; #pragma unroll
;                 for (int bj = 0; bj < 2; ++bj)
; #pragma unroll
;                     for (int n = 0; n < 2; ++n) { const f32x4 bs = *(const f32x4*)(base + off + bj * HALF + n * 16); const f32x4 x1 = bs + acc[ai][bj][m][n] * sr.x * gv[bj][n];
;                         const f32x4 o = x1 * sr.y * g2v[bj][n]; u32x2 w; w.x = cvt_pk_bf16(o[0], o[1]); w.y = cvt_pk_bf16(o[2], o[3]);
;                         if (!dry || x1[0] == 1.2345e38f) { *(f32x4*)(out + off + bj * HALF + n * 16) = x1; *(u32x2*)(xn + off + bj * HALF + n * 16) = w; } }
;                 if (m & 1) asm volatile("" ::: "memory"); }
	v_pk_fma_f32 v[16:17], v[92:93], v[16:17], v[20:21]
	v_pk_fma_f32 v[18:19], v[94:95], v[18:19], v[22:23]
	v_pk_mul_f32 v[20:21], v[40:41], v[16:17] op_sel:[1,0]
	v_pk_mul_f32 v[22:23], v[40:41], v[18:19] op_sel:[1,0]
	v_pk_mul_f32 v[20:21], v[148:149], v[20:21]
	v_pk_mul_f32 v[22:23], v[150:151], v[22:23]
	v_cvt_pk_bf16_f32 v20, v20, v21
	s_nop 0
	v_cvt_pk_bf16_f32 v21, v22, v23
	v_bfi_b32 v240, v238, v248, v16
	v_bfi_b32 v241, v238, v249, v17
	v_bfi_b32 v242, v238, v250, v18
	v_bfi_b32 v243, v238, v251, v19
	v_lshl_add_u64 v[216:217], v[38:39], 0, v[252:253]
	s_nop 0
	v_mov_b32_dpp v244, v240 quad_perm:[1,0,3,2] row_mask:0xf bank_mask:0xf
	v_mov_b32_dpp v245, v241 quad_perm:[1,0,3,2] row_mask:0xf bank_mask:0xf
	v_mov_b32_dpp v246, v242 quad_perm:[1,0,3,2] row_mask:0xf bank_mask:0xf
	v_mov_b32_dpp v247, v243 quad_perm:[1,0,3,2] row_mask:0xf bank_mask:0xf
	v_bfi_b32 v248, v238, v244, v248
	v_bfi_b32 v249, v238, v245, v249
	v_bfi_b32 v250, v238, v246, v250
	v_bfi_b32 v251, v238, v247, v251
	v_bfi_b32 v244, v238, v16, v244
	v_bfi_b32 v245, v238, v17, v245
	v_bfi_b32 v246, v238, v18, v246
	v_bfi_b32 v247, v238, v19, v247
	global_store_dwordx4 v[216:217], v[248:251], off offset:-1536
	global_store_dwordx4 v[216:217], v[244:247], off offset:2560
	v_mov_b32_e32 v222, v20
	v_mov_b32_e32 v223, v21
	v_lshl_add_u64 v[226:227], v[42:43], 0, v[224:225]
	s_nop 0
	v_permlane32_swap_b32_e32 v220, v222
	v_permlane32_swap_b32_e32 v221, v223
	s_nop 1
	v_permlane16_swap_b32_e32 v220, v222
	v_permlane16_swap_b32_e32 v221, v223
	global_store_dwordx4 v[226:227], v[220:223], off offset:256
	ds_read_b64 v[20:21], v33 offset:17792
	v_lshlrev_b64 v[16:17], 10, v[204:205]
	v_lshl_add_u64 v[22:23], v[16:17], 0, v[34:35]
	global_load_dwordx4 v[16:19], v[192:193], off
	s_waitcnt lgkmcnt(0)
	v_pk_mul_f32 v[14:15], v[14:15], v[20:21] op_sel_hi:[1,0]
	v_pk_mul_f32 v[12:13], v[12:13], v[20:21] op_sel_hi:[1,0]
	v_pk_mul_f32 v[8:9], v[8:9], v[20:21] op_sel_hi:[1,0]
	v_pk_mul_f32 v[10:11], v[10:11], v[20:21] op_sel_hi:[1,0]
	v_pk_mul_f32 v[4:5], v[4:5], v[20:21] op_sel_hi:[1,0]
	v_pk_mul_f32 v[6:7], v[6:7], v[20:21] op_sel_hi:[1,0]
	v_pk_mul_f32 v[0:1], v[0:1], v[20:21] op_sel_hi:[1,0]
	v_pk_mul_f32 v[2:3], v[2:3], v[20:21] op_sel_hi:[1,0]
	s_waitcnt vmcnt(0)
	v_pk_fma_f32 v[12:13], v[116:117], v[12:13], v[16:17]
	v_pk_fma_f32 v[14:15], v[118:119], v[14:15], v[18:19]
	v_pk_mul_f32 v[16:17], v[20:21], v[12:13] op_sel:[1,0]
	v_pk_mul_f32 v[18:19], v[20:21], v[14:15] op_sel:[1,0]
	v_pk_mul_f32 v[16:17], v[160:161], v[16:17]
	v_pk_mul_f32 v[18:19], v[162:163], v[18:19]
	v_cvt_pk_bf16_f32 v16, v16, v17
	s_nop 0
	v_cvt_pk_bf16_f32 v17, v18, v19
	v_lshl_add_u64 v[18:19], v[22:23], 2, s[20:21]
	v_lshl_add_u64 v[22:23], v[22:23], 1, s[6:7]
	v_mov_b32_e32 v248, v12
	v_mov_b32_e32 v249, v13
	v_mov_b32_e32 v250, v14
	v_mov_b32_e32 v251, v15
	v_mov_b32_e32 v220, v16
	v_mov_b32_e32 v221, v17
	global_load_dwordx4 v[12:15], v[192:193], off offset:64
	s_waitcnt vmcnt(0)
	v_pk_fma_f32 v[8:9], v[104:105], v[8:9], v[12:13]
	v_pk_fma_f32 v[10:11], v[106:107], v[10:11], v[14:15]
	v_pk_mul_f32 v[12:13], v[20:21], v[8:9] op_sel:[1,0]
	v_pk_mul_f32 v[14:15], v[20:21], v[10:11] op_sel:[1,0]
	v_pk_mul_f32 v[12:13], v[156:157], v[12:13]
	v_pk_mul_f32 v[14:15], v[158:159], v[14:15]
	v_cvt_pk_bf16_f32 v12, v12, v13
	s_nop 0
	v_cvt_pk_bf16_f32 v13, v14, v15
	v_bfi_b32 v240, v238, v248, v8
	v_bfi_b32 v241, v238, v249, v9
	v_bfi_b32 v242, v238, v250, v10
	v_bfi_b32 v243, v238, v251, v11
	v_lshl_add_u64 v[216:217], v[18:19], 0, v[252:253]
	s_nop 0
	v_mov_b32_dpp v244, v240 quad_perm:[1,0,3,2] row_mask:0xf bank_mask:0xf
	v_mov_b32_dpp v245, v241 quad_perm:[1,0,3,2] row_mask:0xf bank_mask:0xf
	v_mov_b32_dpp v246, v242 quad_perm:[1,0,3,2] row_mask:0xf bank_mask:0xf
	v_mov_b32_dpp v247, v243 quad_perm:[1,0,3,2] row_mask:0xf bank_mask:0xf
	v_bfi_b32 v248, v238, v244, v248
	v_bfi_b32 v249, v238, v245, v249
	v_bfi_b32 v250, v238, v246, v250
	v_bfi_b32 v251, v238, v247, v251
	v_bfi_b32 v244, v238, v8, v244
	v_bfi_b32 v245, v238, v9, v245
	v_bfi_b32 v246, v238, v10, v246
	v_bfi_b32 v247, v238, v11, v247
	global_store_dwordx4 v[216:217], v[248:251], off offset:-2048
	global_store_dwordx4 v[216:217], v[244:247], off offset:2048
	v_mov_b32_e32 v222, v12
	v_mov_b32_e32 v223, v13
	v_lshl_add_u64 v[226:227], v[22:23], 0, v[224:225]
	s_nop 0
	v_permlane32_swap_b32_e32 v220, v222
	v_permlane32_swap_b32_e32 v221, v223
	s_nop 1
	v_permlane16_swap_b32_e32 v220, v222
	v_permlane16_swap_b32_e32 v221, v223
	global_store_dwordx4 v[226:227], v[220:223], off
	global_load_dwordx4 v[8:11], v[192:193], off offset:512
	s_waitcnt vmcnt(0)
	v_pk_fma_f32 v[4:5], v[100:101], v[4:5], v[8:9]
	v_pk_fma_f32 v[6:7], v[102:103], v[6:7], v[10:11]
	v_pk_mul_f32 v[8:9], v[20:21], v[4:5] op_sel:[1,0]
	v_pk_mul_f32 v[10:11], v[20:21], v[6:7] op_sel:[1,0]
	v_pk_mul_f32 v[8:9], v[152:153], v[8:9]
	v_pk_mul_f32 v[10:11], v[154:155], v[10:11]
	v_cvt_pk_bf16_f32 v8, v8, v9
	s_nop 0
	v_cvt_pk_bf16_f32 v9, v10, v11
	v_mov_b32_e32 v248, v4
	v_mov_b32_e32 v249, v5
	v_mov_b32_e32 v250, v6
	v_mov_b32_e32 v251, v7
	v_mov_b32_e32 v220, v8
	v_mov_b32_e32 v221, v9
	global_load_dwordx4 v[4:7], v[192:193], off offset:576
	s_waitcnt vmcnt(0)
	v_pk_fma_f32 v[0:1], v[92:93], v[0:1], v[4:5]
	v_pk_fma_f32 v[2:3], v[94:95], v[2:3], v[6:7]
	v_pk_mul_f32 v[4:5], v[20:21], v[0:1] op_sel:[1,0]
	v_pk_mul_f32 v[6:7], v[20:21], v[2:3] op_sel:[1,0]
	v_pk_mul_f32 v[4:5], v[148:149], v[4:5]
	v_pk_mul_f32 v[6:7], v[150:151], v[6:7]
	v_cvt_pk_bf16_f32 v4, v4, v5
	s_nop 0
	v_cvt_pk_bf16_f32 v5, v6, v7
	v_bfi_b32 v240, v238, v248, v0
	v_bfi_b32 v241, v238, v249, v1
	v_bfi_b32 v242, v238, v250, v2
	v_bfi_b32 v243, v238, v251, v3
	v_lshl_add_u64 v[216:217], v[18:19], 0, v[252:253]
	s_nop 0
	v_mov_b32_dpp v244, v240 quad_perm:[1,0,3,2] row_mask:0xf bank_mask:0xf
	v_mov_b32_dpp v245, v241 quad_perm:[1,0,3,2] row_mask:0xf bank_mask:0xf
	v_mov_b32_dpp v246, v242 quad_perm:[1,0,3,2] row_mask:0xf bank_mask:0xf
	v_mov_b32_dpp v247, v243 quad_perm:[1,0,3,2] row_mask:0xf bank_mask:0xf
	v_bfi_b32 v248, v238, v244, v248
	v_bfi_b32 v249, v238, v245, v249
	v_bfi_b32 v250, v238, v246, v250
	v_bfi_b32 v251, v238, v247, v251
	v_bfi_b32 v244, v238, v0, v244
	v_bfi_b32 v245, v238, v1, v245
	v_bfi_b32 v246, v238, v2, v246
	v_bfi_b32 v247, v238, v3, v247
	global_store_dwordx4 v[216:217], v[248:251], off offset:-1536
	global_store_dwordx4 v[216:217], v[244:247], off offset:2560
	v_mov_b32_e32 v222, v4
	v_mov_b32_e32 v223, v5
	v_lshl_add_u64 v[226:227], v[22:23], 0, v[224:225]
	s_nop 0
	v_permlane32_swap_b32_e32 v220, v222
	v_permlane32_swap_b32_e32 v221, v223
	s_nop 1
	v_permlane16_swap_b32_e32 v220, v222
	v_permlane16_swap_b32_e32 v221, v223
	global_store_dwordx4 v[226:227], v[220:223], off offset:256

; __device__ __forceinline__ unsigned cvt_pk_bf16(float lo, float hi) { unsigned r; asm volatile("v_cvt_pk_bf16_f32 %0, %1, %2" : "=v"(r) : "v"(lo), "v"(hi)); return r; }
;     __device__ __forceinline__ void fused(f32x4 (&acc)[2][2][4][2], const Unit& u, int wr, int wc, int fr, int fq, PG8_LAS unsigned char* lds, int wid, int lane) const {
;     ...
;         asm volatile("s_waitcnt lgkmcnt(0)" ::: "memory"); __builtin_amdgcn_s_barrier(); asm volatile("" ::: "memory");
;         f32x4 g2v[2][2];
; #pragma unroll
;         for (int bj = 0; bj < 2; ++bj)
; #pragma unroll
;             for (int n = 0; n < 2; ++n) g2v[bj][n] = *(const f32x4*)(g2 + col0 + bj * HALF + n * 16);
; #pragma unroll
;         for (int ai = 0; ai < 2; ++ai)
; #pragma unroll
;             for (int m = 0; m < 4; ++m) { const int r = ai * HALF + wr * 64 + m * 16 + fr; const f32x2v sr = S[r]; const size_t off = (size_t)(u.pm * BM + r) * 1024 + col0;
; #pragma unroll
;                 for (int bj = 0; bj < 2; ++bj)
; #pragma unroll
;                     for (int n = 0; n < 2; ++n) { const f32x4 bs = *(const f32x4*)(base + off + bj * HALF + n * 16); const f32x4 x1 = bs + acc[ai][bj][m][n] * sr.x * gv[bj][n];
;                         const f32x4 o = x1 * sr.y * g2v[bj][n]; u32x2 w; w.x = cvt_pk_bf16(o[0], o[1]); w.y = cvt_pk_bf16(o[2], o[3]);
;                         if (!dry || x1[0] == 1.2345e38f) { *(f32x4*)(out + off + bj * HALF + n * 16) = x1; *(u32x2*)(xn + off + bj * HALF + n * 16) = w; } }
;                 if (m & 1) asm volatile("" ::: "memory"); }
.LBB0_1115:
	s_or_b64 exec, exec, s[6:7]
	v_and_b32_e32 v238, 1, v228
	v_sub_u32_e32 v238, 0, v238
	v_and_b32_e32 v252, 0xfffff040, v238
	v_add_u32_e32 v252, 0x800, v252
	v_mov_b32_e32 v253, v238
	v_and_b32_e32 v224, 63, v228
	v_lshrrev_b32_e32 v224, 4, v224
	v_lshlrev_b32_e32 v224, 3, v224
	v_mov_b32_e32 v225, 0
	s_ashr_i32 s19, s18, 31
	s_lshl_b64 s[4:5], s[18:19], 14
	s_add_u32 s6, s26, s4
	s_addc_u32 s7, s27, s5
	s_and_b64 s[4:5], s[22:23], exec
	s_cselect_b32 s4, s7, s43
	s_cselect_b32 s5, s6, s42
	s_waitcnt lgkmcnt(0)
	s_barrier
	global_load_dwordx4 v[160:163], v[164:165], off
	v_mov_b32_e32 v148, s5
	v_mov_b32_e32 v149, s4
	v_lshl_add_u64 v[206:207], v[34:35], 2, v[148:149]
	global_load_dwordx4 v[152:155], v[206:207], off
	v_lshl_add_u32 v33, v237, 3, 0
	ds_read_b64 v[208:209], v33 offset:16384
	v_lshlrev_b64 v[148:149], 10, v[166:167]
	s_add_u32 s6, s24, 0xe300000
	v_lshl_add_u64 v[148:149], v[148:149], 0, v[34:35]
	s_addc_u32 s7, s25, 0
	s_waitcnt lgkmcnt(0)
	v_pk_mul_f32 v[210:211], v[128:129], v[208:209] op_sel_hi:[1,0]
	v_pk_mul_f32 v[166:167], v[130:131], v[208:209] op_sel_hi:[1,0]
	v_lshl_add_u64 v[212:213], v[148:149], 1, s[6:7]
	global_load_dwordx4 v[156:159], v[206:207], off offset:64
	global_load_dwordx4 v[148:151], v[206:207], off offset:512
	global_load_dwordx4 v[128:131], v[206:207], off offset:576
	v_pk_mul_f32 v[124:125], v[124:125], v[208:209] op_sel_hi:[1,0]
	v_pk_mul_f32 v[126:127], v[126:127], v[208:209] op_sel_hi:[1,0]
	v_pk_mul_f32 v[120:121], v[120:121], v[208:209] op_sel_hi:[1,0]
	v_pk_mul_f32 v[122:123], v[122:123], v[208:209] op_sel_hi:[1,0]
	v_pk_mul_f32 v[116:117], v[116:117], v[208:209] op_sel_hi:[1,0]
	v_pk_mul_f32 v[118:119], v[118:119], v[208:209] op_sel_hi:[1,0]
	s_waitcnt vmcnt(4)
	v_pk_fma_f32 v[160:161], v[144:145], v[210:211], v[160:161]
	v_pk_fma_f32 v[162:163], v[146:147], v[166:167], v[162:163]
	v_pk_mul_f32 v[166:167], v[208:209], v[160:161] op_sel:[1,0]
	v_pk_mul_f32 v[206:207], v[208:209], v[162:163] op_sel:[1,0]
	s_waitcnt vmcnt(3)
	v_pk_mul_f32 v[166:167], v[152:153], v[166:167]
	v_pk_mul_f32 v[206:207], v[154:155], v[206:207]
	v_cvt_pk_bf16_f32 v166, v166, v167
	s_nop 0
	v_cvt_pk_bf16_f32 v167, v206, v207
	v_mov_b32_e32 v248, v160
	v_mov_b32_e32 v249, v161
	v_mov_b32_e32 v250, v162
	v_mov_b32_e32 v251, v163
	v_mov_b32_e32 v220, v166
	v_mov_b32_e32 v221, v167
	global_load_dwordx4 v[160:163], v[164:165], off offset:64
	s_waitcnt vmcnt(0)
	v_pk_fma_f32 v[124:125], v[140:141], v[124:125], v[160:161]
	v_pk_fma_f32 v[126:127], v[142:143], v[126:127], v[162:163]
	v_pk_mul_f32 v[160:161], v[208:209], v[124:125] op_sel:[1,0]
	v_pk_mul_f32 v[162:163], v[208:209], v[126:127] op_sel:[1,0]
	v_pk_mul_f32 v[160:161], v[156:157], v[160:161]
	v_pk_mul_f32 v[162:163], v[158:159], v[162:163]
	v_cvt_pk_bf16_f32 v160, v160, v161
	s_nop 0
	v_cvt_pk_bf16_f32 v161, v162, v163
	v_bfi_b32 v240, v238, v248, v124
	v_bfi_b32 v241, v238, v249, v125
	v_bfi_b32 v242, v238, v250, v126
	v_bfi_b32 v243, v238, v251, v127
	v_lshl_add_u64 v[216:217], v[164:165], 0, v[252:253]
	s_nop 0
	v_mov_b32_dpp v244, v240 quad_perm:[1,0,3,2] row_mask:0xf bank_mask:0xf
	v_mov_b32_dpp v245, v241 quad_perm:[1,0,3,2] row_mask:0xf bank_mask:0xf
	v_mov_b32_dpp v246, v242 quad_perm:[1,0,3,2] row_mask:0xf bank_mask:0xf
	v_mov_b32_dpp v247, v243 quad_perm:[1,0,3,2] row_mask:0xf bank_mask:0xf
	v_bfi_b32 v248, v238, v244, v248
	v_bfi_b32 v249, v238, v245, v249
	v_bfi_b32 v250, v238, v246, v250
	v_bfi_b32 v251, v238, v247, v251
	v_bfi_b32 v244, v238, v124, v244
	v_bfi_b32 v245, v238, v125, v245
	v_bfi_b32 v246, v238, v126, v246
	v_bfi_b32 v247, v238, v127, v247
	global_store_dwordx4 v[216:217], v[248:251], off offset:-2048
	global_store_dwordx4 v[216:217], v[244:247], off offset:2048
	v_mov_b32_e32 v222, v160
	v_mov_b32_e32 v223, v161
	v_lshl_add_u64 v[226:227], v[212:213], 0, v[224:225]
	s_nop 0
	v_permlane32_swap_b32_e32 v220, v222
	v_permlane32_swap_b32_e32 v221, v223
	s_nop 1
	v_permlane16_swap_b32_e32 v220, v222
	v_permlane16_swap_b32_e32 v221, v223
	global_store_dwordx4 v[226:227], v[220:223], off
	global_load_dwordx4 v[124:127], v[164:165], off offset:512
	s_waitcnt vmcnt(0)
	v_pk_fma_f32 v[120:121], v[136:137], v[120:121], v[124:125]
	v_pk_fma_f32 v[122:123], v[138:139], v[122:123], v[126:127]
	v_pk_mul_f32 v[124:125], v[208:209], v[120:121] op_sel:[1,0]
	v_pk_mul_f32 v[126:127], v[208:209], v[122:123] op_sel:[1,0]
	v_pk_mul_f32 v[124:125], v[148:149], v[124:125]
	v_pk_mul_f32 v[126:127], v[150:151], v[126:127]
	v_cvt_pk_bf16_f32 v124, v124, v125
	s_nop 0
	v_cvt_pk_bf16_f32 v125, v126, v127
	v_mov_b32_e32 v248, v120
	v_mov_b32_e32 v249, v121
	v_mov_b32_e32 v250, v122
	v_mov_b32_e32 v251, v123
	v_mov_b32_e32 v220, v124
	v_mov_b32_e32 v221, v125
	global_load_dwordx4 v[120:123], v[164:165], off offset:576
	s_waitcnt vmcnt(0)
; __device__ __forceinline__ unsigned cvt_pk_bf16(float lo, float hi) { unsigned r; asm volatile("v_cvt_pk_bf16_f32 %0, %1, %2" : "=v"(r) : "v"(lo), "v"(hi)); return r; }
;     __device__ __forceinline__ void fused(f32x4 (&acc)[2][2][4][2], const Unit& u, int wr, int wc, int fr, int fq, PG8_LAS unsigned char* lds, int wid, int lane) const {
;     ...
;         for (int ai = 0; ai < 2; ++ai)
; #pragma unroll
;             for (int m = 0; m < 4; ++m) { const int r = ai * HALF + wr * 64 + m * 16 + fr; const f32x2v sr = S[r]; const size_t off = (size_t)(u.pm * BM + r) * 1024 + col0;
; #pragma unroll
;                 for (int bj = 0; bj < 2; ++bj)
; #pragma unroll
;                     for (int n = 0; n < 2; ++n) { const f32x4 bs = *(const f32x4*)(base + off + bj * HALF + n * 16); const f32x4 x1 = bs + acc[ai][bj][m][n] * sr.x * gv[bj][n];
;                         const f32x4 o = x1 * sr.y * g2v[bj][n]; u32x2 w; w.x = cvt_pk_bf16(o[0], o[1]); w.y = cvt_pk_bf16(o[2], o[3]);
;                         if (!dry || x1[0] == 1.2345e38f) { *(f32x4*)(out + off + bj * HALF + n * 16) = x1; *(u32x2*)(xn + off + bj * HALF + n * 16) = w; } }
;                 if (m & 1) asm volatile("" ::: "memory"); }
	v_pk_fma_f32 v[116:117], v[132:133], v[116:117], v[120:121]
	v_pk_fma_f32 v[118:119], v[134:135], v[118:119], v[122:123]
	v_pk_mul_f32 v[120:121], v[208:209], v[116:117] op_sel:[1,0]
	v_pk_mul_f32 v[122:123], v[208:209], v[118:119] op_sel:[1,0]
	v_pk_mul_f32 v[120:121], v[128:129], v[120:121]
	v_pk_mul_f32 v[122:123], v[130:131], v[122:123]
	v_cvt_pk_bf16_f32 v120, v120, v121
	s_nop 0
	v_cvt_pk_bf16_f32 v121, v122, v123
	v_bfi_b32 v240, v238, v248, v116
	v_bfi_b32 v241, v238, v249, v117
	v_bfi_b32 v242, v238, v250, v118
	v_bfi_b32 v243, v238, v251, v119
	v_lshl_add_u64 v[216:217], v[164:165], 0, v[252:253]
	s_nop 0
	v_mov_b32_dpp v244, v240 quad_perm:[1,0,3,2] row_mask:0xf bank_mask:0xf
	v_mov_b32_dpp v245, v241 quad_perm:[1,0,3,2] row_mask:0xf bank_mask:0xf
	v_mov_b32_dpp v246, v242 quad_perm:[1,0,3,2] row_mask:0xf bank_mask:0xf
	v_mov_b32_dpp v247, v243 quad_perm:[1,0,3,2] row_mask:0xf bank_mask:0xf
	v_bfi_b32 v248, v238, v244, v248
	v_bfi_b32 v249, v238, v245, v249
	v_bfi_b32 v250, v238, v246, v250
	v_bfi_b32 v251, v238, v247, v251
	v_bfi_b32 v244, v238, v116, v244
	v_bfi_b32 v245, v238, v117, v245
	v_bfi_b32 v246, v238, v118, v246
	v_bfi_b32 v247, v238, v119, v247
	global_store_dwordx4 v[216:217], v[248:251], off offset:-1536
	global_store_dwordx4 v[216:217], v[244:247], off offset:2560
	v_mov_b32_e32 v222, v120
	v_mov_b32_e32 v223, v121
	v_lshl_add_u64 v[226:227], v[212:213], 0, v[224:225]
	s_nop 0
	v_permlane32_swap_b32_e32 v220, v222
	v_permlane32_swap_b32_e32 v221, v223
	s_nop 1
	v_permlane16_swap_b32_e32 v220, v222
	v_permlane16_swap_b32_e32 v221, v223
	global_store_dwordx4 v[226:227], v[220:223], off offset:256
	global_load_dwordx4 v[116:119], v[168:169], off
	ds_read_b64 v[120:121], v33 offset:16512
	v_lshlrev_b64 v[122:123], 10, v[170:171]
	v_lshl_add_u64 v[122:123], v[122:123], 0, v[34:35]
	v_lshl_add_u64 v[122:123], v[122:123], 1, s[6:7]
	s_waitcnt lgkmcnt(0)
	v_pk_mul_f32 v[112:113], v[112:113], v[120:121] op_sel_hi:[1,0]
	v_pk_mul_f32 v[114:115], v[114:115], v[120:121] op_sel_hi:[1,0]
	v_pk_mul_f32 v[108:109], v[108:109], v[120:121] op_sel_hi:[1,0]
	v_pk_mul_f32 v[110:111], v[110:111], v[120:121] op_sel_hi:[1,0]
	v_pk_mul_f32 v[104:105], v[104:105], v[120:121] op_sel_hi:[1,0]
	v_pk_mul_f32 v[106:107], v[106:107], v[120:121] op_sel_hi:[1,0]
	v_pk_mul_f32 v[100:101], v[100:101], v[120:121] op_sel_hi:[1,0]
	v_pk_mul_f32 v[102:103], v[102:103], v[120:121] op_sel_hi:[1,0]
	s_waitcnt vmcnt(0)
	v_pk_fma_f32 v[112:113], v[144:145], v[112:113], v[116:117]
	v_pk_fma_f32 v[114:115], v[146:147], v[114:115], v[118:119]
	v_pk_mul_f32 v[116:117], v[120:121], v[112:113] op_sel:[1,0]
	v_pk_mul_f32 v[118:119], v[120:121], v[114:115] op_sel:[1,0]
	v_pk_mul_f32 v[116:117], v[152:153], v[116:117]
	v_pk_mul_f32 v[118:119], v[154:155], v[118:119]
	v_cvt_pk_bf16_f32 v116, v116, v117
	s_nop 0
	v_cvt_pk_bf16_f32 v117, v118, v119
	v_mov_b32_e32 v248, v112
	v_mov_b32_e32 v249, v113
	v_mov_b32_e32 v250, v114
	v_mov_b32_e32 v251, v115
	v_mov_b32_e32 v220, v116
	v_mov_b32_e32 v221, v117
	global_load_dwordx4 v[112:115], v[168:169], off offset:64
	s_waitcnt vmcnt(0)
	v_pk_fma_f32 v[108:109], v[140:141], v[108:109], v[112:113]
	v_pk_fma_f32 v[110:111], v[142:143], v[110:111], v[114:115]
	v_pk_mul_f32 v[112:113], v[120:121], v[108:109] op_sel:[1,0]
	v_pk_mul_f32 v[114:115], v[120:121], v[110:111] op_sel:[1,0]
	v_pk_mul_f32 v[112:113], v[156:157], v[112:113]
	v_pk_mul_f32 v[114:115], v[158:159], v[114:115]
	v_cvt_pk_bf16_f32 v112, v112, v113
	s_nop 0
	v_cvt_pk_bf16_f32 v113, v114, v115
	v_bfi_b32 v240, v238, v248, v108
	v_bfi_b32 v241, v238, v249, v109
	v_bfi_b32 v242, v238, v250, v110
	v_bfi_b32 v243, v238, v251, v111
	v_lshl_add_u64 v[216:217], v[168:169], 0, v[252:253]
	s_nop 0
	v_mov_b32_dpp v244, v240 quad_perm:[1,0,3,2] row_mask:0xf bank_mask:0xf
	v_mov_b32_dpp v245, v241 quad_perm:[1,0,3,2] row_mask:0xf bank_mask:0xf
	v_mov_b32_dpp v246, v242 quad_perm:[1,0,3,2] row_mask:0xf bank_mask:0xf
	v_mov_b32_dpp v247, v243 quad_perm:[1,0,3,2] row_mask:0xf bank_mask:0xf
	v_bfi_b32 v248, v238, v244, v248
	v_bfi_b32 v249, v238, v245, v249
	v_bfi_b32 v250, v238, v246, v250
	v_bfi_b32 v251, v238, v247, v251
	v_bfi_b32 v244, v238, v108, v244
	v_bfi_b32 v245, v238, v109, v245
	v_bfi_b32 v246, v238, v110, v246
	v_bfi_b32 v247, v238, v111, v247
	global_store_dwordx4 v[216:217], v[248:251], off offset:-2048
	global_store_dwordx4 v[216:217], v[244:247], off offset:2048
	v_mov_b32_e32 v222, v112
	v_mov_b32_e32 v223, v113
	v_lshl_add_u64 v[226:227], v[122:123], 0, v[224:225]
	s_nop 0
	v_permlane32_swap_b32_e32 v220, v222
	v_permlane32_swap_b32_e32 v221, v223
	s_nop 1
	v_permlane16_swap_b32_e32 v220, v222
	v_permlane16_swap_b32_e32 v221, v223
	global_store_dwordx4 v[226:227], v[220:223], off
	global_load_dwordx4 v[108:111], v[168:169], off offset:512
	s_waitcnt vmcnt(0)
	v_pk_fma_f32 v[104:105], v[136:137], v[104:105], v[108:109]
	v_pk_fma_f32 v[106:107], v[138:139], v[106:107], v[110:111]
	v_pk_mul_f32 v[108:109], v[120:121], v[104:105] op_sel:[1,0]
	v_pk_mul_f32 v[110:111], v[120:121], v[106:107] op_sel:[1,0]
	v_pk_mul_f32 v[108:109], v[148:149], v[108:109]
	v_pk_mul_f32 v[110:111], v[150:151], v[110:111]
	v_cvt_pk_bf16_f32 v108, v108, v109
	s_nop 0
	v_cvt_pk_bf16_f32 v109, v110, v111
	v_mov_b32_e32 v248, v104
	v_mov_b32_e32 v249, v105
	v_mov_b32_e32 v250, v106
	v_mov_b32_e32 v251, v107
	v_mov_b32_e32 v220, v108
	v_mov_b32_e32 v221, v109
	global_load_dwordx4 v[104:107], v[168:169], off offset:576
	s_waitcnt vmcnt(0)
; __device__ __forceinline__ unsigned cvt_pk_bf16(float lo, float hi) { unsigned r; asm volatile("v_cvt_pk_bf16_f32 %0, %1, %2" : "=v"(r) : "v"(lo), "v"(hi)); return r; }
;     __device__ __forceinline__ void fused(f32x4 (&acc)[2][2][4][2], const Unit& u, int wr, int wc, int fr, int fq, PG8_LAS unsigned char* lds, int wid, int lane) const {
;     ...
;         for (int ai = 0; ai < 2; ++ai)
; #pragma unroll
;             for (int m = 0; m < 4; ++m) { const int r = ai * HALF + wr * 64 + m * 16 + fr; const f32x2v sr = S[r]; const size_t off = (size_t)(u.pm * BM + r) * 1024 + col0;
; #pragma unroll
;                 for (int bj = 0; bj < 2; ++bj)
; #pragma unroll
;                     for (int n = 0; n < 2; ++n) { const f32x4 bs = *(const f32x4*)(base + off + bj * HALF + n * 16); const f32x4 x1 = bs + acc[ai][bj][m][n] * sr.x * gv[bj][n];
;                         const f32x4 o = x1 * sr.y * g2v[bj][n]; u32x2 w; w.x = cvt_pk_bf16(o[0], o[1]); w.y = cvt_pk_bf16(o[2], o[3]);
;                         if (!dry || x1[0] == 1.2345e38f) { *(f32x4*)(out + off + bj * HALF + n * 16) = x1; *(u32x2*)(xn + off + bj * HALF + n * 16) = w; } }
;                 if (m & 1) asm volatile("" ::: "memory"); }
	v_pk_fma_f32 v[100:101], v[132:133], v[100:101], v[104:105]
	v_pk_fma_f32 v[102:103], v[134:135], v[102:103], v[106:107]
	v_pk_mul_f32 v[104:105], v[120:121], v[100:101] op_sel:[1,0]
	v_pk_mul_f32 v[106:107], v[120:121], v[102:103] op_sel:[1,0]
	v_pk_mul_f32 v[104:105], v[128:129], v[104:105]
	v_pk_mul_f32 v[106:107], v[130:131], v[106:107]
	v_cvt_pk_bf16_f32 v104, v104, v105
	s_nop 0
	v_cvt_pk_bf16_f32 v105, v106, v107
	v_bfi_b32 v240, v238, v248, v100
	v_bfi_b32 v241, v238, v249, v101
	v_bfi_b32 v242, v238, v250, v102
	v_bfi_b32 v243, v238, v251, v103
	v_lshl_add_u64 v[216:217], v[168:169], 0, v[252:253]
	s_nop 0
	v_mov_b32_dpp v244, v240 quad_perm:[1,0,3,2] row_mask:0xf bank_mask:0xf
	v_mov_b32_dpp v245, v241 quad_perm:[1,0,3,2] row_mask:0xf bank_mask:0xf
	v_mov_b32_dpp v246, v242 quad_perm:[1,0,3,2] row_mask:0xf bank_mask:0xf
	v_mov_b32_dpp v247, v243 quad_perm:[1,0,3,2] row_mask:0xf bank_mask:0xf
	v_bfi_b32 v248, v238, v244, v248
	v_bfi_b32 v249, v238, v245, v249
	v_bfi_b32 v250, v238, v246, v250
	v_bfi_b32 v251, v238, v247, v251
	v_bfi_b32 v244, v238, v100, v244
	v_bfi_b32 v245, v238, v101, v245
	v_bfi_b32 v246, v238, v102, v246
	v_bfi_b32 v247, v238, v103, v247
	global_store_dwordx4 v[216:217], v[248:251], off offset:-1536
	global_store_dwordx4 v[216:217], v[244:247], off offset:2560
	v_mov_b32_e32 v222, v104
	v_mov_b32_e32 v223, v105
	v_lshl_add_u64 v[226:227], v[122:123], 0, v[224:225]
	s_nop 0
	v_permlane32_swap_b32_e32 v220, v222
	v_permlane32_swap_b32_e32 v221, v223
	s_nop 1
	v_permlane16_swap_b32_e32 v220, v222
	v_permlane16_swap_b32_e32 v221, v223
	global_store_dwordx4 v[226:227], v[220:223], off offset:256
	global_load_dwordx4 v[100:103], v[172:173], off
	ds_read_b64 v[104:105], v33 offset:16640
	v_lshlrev_b64 v[106:107], 10, v[174:175]
	v_lshl_add_u64 v[106:107], v[106:107], 0, v[34:35]
	v_lshl_add_u64 v[106:107], v[106:107], 1, s[6:7]
	s_waitcnt lgkmcnt(0)
	v_pk_mul_f32 v[96:97], v[96:97], v[104:105] op_sel_hi:[1,0]
	v_pk_mul_f32 v[98:99], v[98:99], v[104:105] op_sel_hi:[1,0]
	v_pk_mul_f32 v[92:93], v[92:93], v[104:105] op_sel_hi:[1,0]
	v_pk_mul_f32 v[94:95], v[94:95], v[104:105] op_sel_hi:[1,0]
	v_pk_mul_f32 v[88:89], v[88:89], v[104:105] op_sel_hi:[1,0]
	v_pk_mul_f32 v[90:91], v[90:91], v[104:105] op_sel_hi:[1,0]
	v_pk_mul_f32 v[84:85], v[84:85], v[104:105] op_sel_hi:[1,0]
	v_pk_mul_f32 v[86:87], v[86:87], v[104:105] op_sel_hi:[1,0]
	s_waitcnt vmcnt(0)
	v_pk_fma_f32 v[96:97], v[144:145], v[96:97], v[100:101]
	v_pk_fma_f32 v[98:99], v[146:147], v[98:99], v[102:103]
	v_pk_mul_f32 v[100:101], v[104:105], v[96:97] op_sel:[1,0]
	v_pk_mul_f32 v[102:103], v[104:105], v[98:99] op_sel:[1,0]
	v_pk_mul_f32 v[100:101], v[152:153], v[100:101]
	v_pk_mul_f32 v[102:103], v[154:155], v[102:103]
	v_cvt_pk_bf16_f32 v100, v100, v101
	s_nop 0
	v_cvt_pk_bf16_f32 v101, v102, v103
	v_mov_b32_e32 v248, v96
	v_mov_b32_e32 v249, v97
	v_mov_b32_e32 v250, v98
	v_mov_b32_e32 v251, v99
	v_mov_b32_e32 v220, v100
	v_mov_b32_e32 v221, v101
	global_load_dwordx4 v[96:99], v[172:173], off offset:64
	s_waitcnt vmcnt(0)
	v_pk_fma_f32 v[92:93], v[140:141], v[92:93], v[96:97]
	v_pk_fma_f32 v[94:95], v[142:143], v[94:95], v[98:99]
	v_pk_mul_f32 v[96:97], v[104:105], v[92:93] op_sel:[1,0]
	v_pk_mul_f32 v[98:99], v[104:105], v[94:95] op_sel:[1,0]
	v_pk_mul_f32 v[96:97], v[156:157], v[96:97]
	v_pk_mul_f32 v[98:99], v[158:159], v[98:99]
	v_cvt_pk_bf16_f32 v96, v96, v97
	s_nop 0
	v_cvt_pk_bf16_f32 v97, v98, v99
	v_bfi_b32 v240, v238, v248, v92
	v_bfi_b32 v241, v238, v249, v93
	v_bfi_b32 v242, v238, v250, v94
	v_bfi_b32 v243, v238, v251, v95
	v_lshl_add_u64 v[216:217], v[172:173], 0, v[252:253]
	s_nop 0
	v_mov_b32_dpp v244, v240 quad_perm:[1,0,3,2] row_mask:0xf bank_mask:0xf
	v_mov_b32_dpp v245, v241 quad_perm:[1,0,3,2] row_mask:0xf bank_mask:0xf
	v_mov_b32_dpp v246, v242 quad_perm:[1,0,3,2] row_mask:0xf bank_mask:0xf
	v_mov_b32_dpp v247, v243 quad_perm:[1,0,3,2] row_mask:0xf bank_mask:0xf
	v_bfi_b32 v248, v238, v244, v248
	v_bfi_b32 v249, v238, v245, v249
	v_bfi_b32 v250, v238, v246, v250
	v_bfi_b32 v251, v238, v247, v251
	v_bfi_b32 v244, v238, v92, v244
	v_bfi_b32 v245, v238, v93, v245
	v_bfi_b32 v246, v238, v94, v246
	v_bfi_b32 v247, v238, v95, v247
	global_store_dwordx4 v[216:217], v[248:251], off offset:-2048
	global_store_dwordx4 v[216:217], v[244:247], off offset:2048
	v_mov_b32_e32 v222, v96
	v_mov_b32_e32 v223, v97
	v_lshl_add_u64 v[226:227], v[106:107], 0, v[224:225]
	s_nop 0
	v_permlane32_swap_b32_e32 v220, v222
	v_permlane32_swap_b32_e32 v221, v223
	s_nop 1
	v_permlane16_swap_b32_e32 v220, v222
	v_permlane16_swap_b32_e32 v221, v223
	global_store_dwordx4 v[226:227], v[220:223], off
	global_load_dwordx4 v[92:95], v[172:173], off offset:512
	s_waitcnt vmcnt(0)
	v_pk_fma_f32 v[88:89], v[136:137], v[88:89], v[92:93]
	v_pk_fma_f32 v[90:91], v[138:139], v[90:91], v[94:95]
	v_pk_mul_f32 v[92:93], v[104:105], v[88:89] op_sel:[1,0]
	v_pk_mul_f32 v[94:95], v[104:105], v[90:91] op_sel:[1,0]
	v_pk_mul_f32 v[92:93], v[148:149], v[92:93]
	v_pk_mul_f32 v[94:95], v[150:151], v[94:95]
	v_cvt_pk_bf16_f32 v92, v92, v93
	s_nop 0
	v_cvt_pk_bf16_f32 v93, v94, v95
	v_mov_b32_e32 v248, v88
	v_mov_b32_e32 v249, v89
	v_mov_b32_e32 v250, v90
	v_mov_b32_e32 v251, v91
	v_mov_b32_e32 v220, v92
	v_mov_b32_e32 v221, v93
	global_load_dwordx4 v[88:91], v[172:173], off offset:576
	s_waitcnt vmcnt(0)
; __device__ __forceinline__ unsigned cvt_pk_bf16(float lo, float hi) { unsigned r; asm volatile("v_cvt_pk_bf16_f32 %0, %1, %2" : "=v"(r) : "v"(lo), "v"(hi)); return r; }
;     __device__ __forceinline__ void fused(f32x4 (&acc)[2][2][4][2], const Unit& u, int wr, int wc, int fr, int fq, PG8_LAS unsigned char* lds, int wid, int lane) const {
;     ...
;         for (int ai = 0; ai < 2; ++ai)
; #pragma unroll
;             for (int m = 0; m < 4; ++m) { const int r = ai * HALF + wr * 64 + m * 16 + fr; const f32x2v sr = S[r]; const size_t off = (size_t)(u.pm * BM + r) * 1024 + col0;
; #pragma unroll
;                 for (int bj = 0; bj < 2; ++bj)
; #pragma unroll
;                     for (int n = 0; n < 2; ++n) { const f32x4 bs = *(const f32x4*)(base + off + bj * HALF + n * 16); const f32x4 x1 = bs + acc[ai][bj][m][n] * sr.x * gv[bj][n];
;                         const f32x4 o = x1 * sr.y * g2v[bj][n]; u32x2 w; w.x = cvt_pk_bf16(o[0], o[1]); w.y = cvt_pk_bf16(o[2], o[3]);
;                         if (!dry || x1[0] == 1.2345e38f) { *(f32x4*)(out + off + bj * HALF + n * 16) = x1; *(u32x2*)(xn + off + bj * HALF + n * 16) = w; } }
;                 if (m & 1) asm volatile("" ::: "memory"); }
	v_pk_fma_f32 v[84:85], v[132:133], v[84:85], v[88:89]
	v_pk_fma_f32 v[86:87], v[134:135], v[86:87], v[90:91]
	v_pk_mul_f32 v[88:89], v[104:105], v[84:85] op_sel:[1,0]
	v_pk_mul_f32 v[90:91], v[104:105], v[86:87] op_sel:[1,0]
	v_pk_mul_f32 v[88:89], v[128:129], v[88:89]
	v_pk_mul_f32 v[90:91], v[130:131], v[90:91]
	v_cvt_pk_bf16_f32 v88, v88, v89
	s_nop 0
	v_cvt_pk_bf16_f32 v89, v90, v91
	v_bfi_b32 v240, v238, v248, v84
	v_bfi_b32 v241, v238, v249, v85
	v_bfi_b32 v242, v238, v250, v86
	v_bfi_b32 v243, v238, v251, v87
	v_lshl_add_u64 v[216:217], v[172:173], 0, v[252:253]
	s_nop 0
	v_mov_b32_dpp v244, v240 quad_perm:[1,0,3,2] row_mask:0xf bank_mask:0xf
	v_mov_b32_dpp v245, v241 quad_perm:[1,0,3,2] row_mask:0xf bank_mask:0xf
	v_mov_b32_dpp v246, v242 quad_perm:[1,0,3,2] row_mask:0xf bank_mask:0xf
	v_mov_b32_dpp v247, v243 quad_perm:[1,0,3,2] row_mask:0xf bank_mask:0xf
	v_bfi_b32 v248, v238, v244, v248
	v_bfi_b32 v249, v238, v245, v249
	v_bfi_b32 v250, v238, v246, v250
	v_bfi_b32 v251, v238, v247, v251
	v_bfi_b32 v244, v238, v84, v244
	v_bfi_b32 v245, v238, v85, v245
	v_bfi_b32 v246, v238, v86, v246
	v_bfi_b32 v247, v238, v87, v247
	global_store_dwordx4 v[216:217], v[248:251], off offset:-1536
	global_store_dwordx4 v[216:217], v[244:247], off offset:2560
	v_mov_b32_e32 v222, v88
	v_mov_b32_e32 v223, v89
	v_lshl_add_u64 v[226:227], v[106:107], 0, v[224:225]
	s_nop 0
	v_permlane32_swap_b32_e32 v220, v222
	v_permlane32_swap_b32_e32 v221, v223
	s_nop 1
	v_permlane16_swap_b32_e32 v220, v222
	v_permlane16_swap_b32_e32 v221, v223
	global_store_dwordx4 v[226:227], v[220:223], off offset:256
	global_load_dwordx4 v[84:87], v[176:177], off
	ds_read_b64 v[88:89], v33 offset:16768
	v_lshlrev_b64 v[90:91], 10, v[178:179]
	v_lshl_add_u64 v[90:91], v[90:91], 0, v[34:35]
	v_lshl_add_u64 v[90:91], v[90:91], 1, s[6:7]
	s_waitcnt lgkmcnt(0)
	v_pk_mul_f32 v[80:81], v[80:81], v[88:89] op_sel_hi:[1,0]
	v_pk_mul_f32 v[82:83], v[82:83], v[88:89] op_sel_hi:[1,0]
	v_pk_mul_f32 v[76:77], v[76:77], v[88:89] op_sel_hi:[1,0]
	v_pk_mul_f32 v[78:79], v[78:79], v[88:89] op_sel_hi:[1,0]
	v_pk_mul_f32 v[72:73], v[72:73], v[88:89] op_sel_hi:[1,0]
	v_pk_mul_f32 v[74:75], v[74:75], v[88:89] op_sel_hi:[1,0]
	v_pk_mul_f32 v[68:69], v[68:69], v[88:89] op_sel_hi:[1,0]
	v_pk_mul_f32 v[70:71], v[70:71], v[88:89] op_sel_hi:[1,0]
	s_waitcnt vmcnt(0)
	v_pk_fma_f32 v[80:81], v[144:145], v[80:81], v[84:85]
	v_pk_fma_f32 v[82:83], v[146:147], v[82:83], v[86:87]
	v_pk_mul_f32 v[84:85], v[88:89], v[80:81] op_sel:[1,0]
	v_pk_mul_f32 v[86:87], v[88:89], v[82:83] op_sel:[1,0]
	v_pk_mul_f32 v[84:85], v[152:153], v[84:85]
	v_pk_mul_f32 v[86:87], v[154:155], v[86:87]
	v_cvt_pk_bf16_f32 v84, v84, v85
	s_nop 0
	v_cvt_pk_bf16_f32 v85, v86, v87
	v_mov_b32_e32 v248, v80
	v_mov_b32_e32 v249, v81
	v_mov_b32_e32 v250, v82
	v_mov_b32_e32 v251, v83
	v_mov_b32_e32 v220, v84
	v_mov_b32_e32 v221, v85
	global_load_dwordx4 v[80:83], v[176:177], off offset:64
	s_waitcnt vmcnt(0)
	v_pk_fma_f32 v[76:77], v[140:141], v[76:77], v[80:81]
	v_pk_fma_f32 v[78:79], v[142:143], v[78:79], v[82:83]
	v_pk_mul_f32 v[80:81], v[88:89], v[76:77] op_sel:[1,0]
	v_pk_mul_f32 v[82:83], v[88:89], v[78:79] op_sel:[1,0]
	v_pk_mul_f32 v[80:81], v[156:157], v[80:81]
	v_pk_mul_f32 v[82:83], v[158:159], v[82:83]
	v_cvt_pk_bf16_f32 v80, v80, v81
	s_nop 0
	v_cvt_pk_bf16_f32 v81, v82, v83
	v_bfi_b32 v240, v238, v248, v76
	v_bfi_b32 v241, v238, v249, v77
	v_bfi_b32 v242, v238, v250, v78
	v_bfi_b32 v243, v238, v251, v79
	v_lshl_add_u64 v[216:217], v[176:177], 0, v[252:253]
	s_nop 0
	v_mov_b32_dpp v244, v240 quad_perm:[1,0,3,2] row_mask:0xf bank_mask:0xf
	v_mov_b32_dpp v245, v241 quad_perm:[1,0,3,2] row_mask:0xf bank_mask:0xf
	v_mov_b32_dpp v246, v242 quad_perm:[1,0,3,2] row_mask:0xf bank_mask:0xf
	v_mov_b32_dpp v247, v243 quad_perm:[1,0,3,2] row_mask:0xf bank_mask:0xf
	v_bfi_b32 v248, v238, v244, v248
	v_bfi_b32 v249, v238, v245, v249
	v_bfi_b32 v250, v238, v246, v250
	v_bfi_b32 v251, v238, v247, v251
	v_bfi_b32 v244, v238, v76, v244
	v_bfi_b32 v245, v238, v77, v245
	v_bfi_b32 v246, v238, v78, v246
	v_bfi_b32 v247, v238, v79, v247
	global_store_dwordx4 v[216:217], v[248:251], off offset:-2048
	global_store_dwordx4 v[216:217], v[244:247], off offset:2048
	v_mov_b32_e32 v222, v80
	v_mov_b32_e32 v223, v81
	v_lshl_add_u64 v[226:227], v[90:91], 0, v[224:225]
	s_nop 0
	v_permlane32_swap_b32_e32 v220, v222
	v_permlane32_swap_b32_e32 v221, v223
	s_nop 1
	v_permlane16_swap_b32_e32 v220, v222
	v_permlane16_swap_b32_e32 v221, v223
	global_store_dwordx4 v[226:227], v[220:223], off
	global_load_dwordx4 v[76:79], v[176:177], off offset:512
	s_waitcnt vmcnt(0)
	v_pk_fma_f32 v[72:73], v[136:137], v[72:73], v[76:77]
	v_pk_fma_f32 v[74:75], v[138:139], v[74:75], v[78:79]
	v_pk_mul_f32 v[76:77], v[88:89], v[72:73] op_sel:[1,0]
	v_pk_mul_f32 v[78:79], v[88:89], v[74:75] op_sel:[1,0]
	v_pk_mul_f32 v[76:77], v[148:149], v[76:77]
	v_pk_mul_f32 v[78:79], v[150:151], v[78:79]
	v_cvt_pk_bf16_f32 v76, v76, v77
	s_nop 0
	v_cvt_pk_bf16_f32 v77, v78, v79
	v_mov_b32_e32 v248, v72
	v_mov_b32_e32 v249, v73
	v_mov_b32_e32 v250, v74
	v_mov_b32_e32 v251, v75
	v_mov_b32_e32 v220, v76
	v_mov_b32_e32 v221, v77
	global_load_dwordx4 v[72:75], v[176:177], off offset:576
	s_waitcnt vmcnt(0)
; __device__ __forceinline__ unsigned cvt_pk_bf16(float lo, float hi) { unsigned r; asm volatile("v_cvt_pk_bf16_f32 %0, %1, %2" : "=v"(r) : "v"(lo), "v"(hi)); return r; }
;     __device__ __forceinline__ void fused(f32x4 (&acc)[2][2][4][2], const Unit& u, int wr, int wc, int fr, int fq, PG8_LAS unsigned char* lds, int wid, int lane) const {
;     ...
;         for (int ai = 0; ai < 2; ++ai)
; #pragma unroll
;             for (int m = 0; m < 4; ++m) { const int r = ai * HALF + wr * 64 + m * 16 + fr; const f32x2v sr = S[r]; const size_t off = (size_t)(u.pm * BM + r) * 1024 + col0;
; #pragma unroll
;                 for (int bj = 0; bj < 2; ++bj)
; #pragma unroll
;                     for (int n = 0; n < 2; ++n) { const f32x4 bs = *(const f32x4*)(base + off + bj * HALF + n * 16); const f32x4 x1 = bs + acc[ai][bj][m][n] * sr.x * gv[bj][n];
;                         const f32x4 o = x1 * sr.y * g2v[bj][n]; u32x2 w; w.x = cvt_pk_bf16(o[0], o[1]); w.y = cvt_pk_bf16(o[2], o[3]);
;                         if (!dry || x1[0] == 1.2345e38f) { *(f32x4*)(out + off + bj * HALF + n * 16) = x1; *(u32x2*)(xn + off + bj * HALF + n * 16) = w; } }
;                 if (m & 1) asm volatile("" ::: "memory"); }
	v_pk_fma_f32 v[68:69], v[132:133], v[68:69], v[72:73]
	v_pk_fma_f32 v[70:71], v[134:135], v[70:71], v[74:75]
	v_pk_mul_f32 v[72:73], v[88:89], v[68:69] op_sel:[1,0]
	v_pk_mul_f32 v[74:75], v[88:89], v[70:71] op_sel:[1,0]
	v_pk_mul_f32 v[72:73], v[128:129], v[72:73]
	v_pk_mul_f32 v[74:75], v[130:131], v[74:75]
	v_cvt_pk_bf16_f32 v72, v72, v73
	s_nop 0
	v_cvt_pk_bf16_f32 v73, v74, v75
	v_bfi_b32 v240, v238, v248, v68
	v_bfi_b32 v241, v238, v249, v69
	v_bfi_b32 v242, v238, v250, v70
	v_bfi_b32 v243, v238, v251, v71
	v_lshl_add_u64 v[216:217], v[176:177], 0, v[252:253]
	s_nop 0
	v_mov_b32_dpp v244, v240 quad_perm:[1,0,3,2] row_mask:0xf bank_mask:0xf
	v_mov_b32_dpp v245, v241 quad_perm:[1,0,3,2] row_mask:0xf bank_mask:0xf
	v_mov_b32_dpp v246, v242 quad_perm:[1,0,3,2] row_mask:0xf bank_mask:0xf
	v_mov_b32_dpp v247, v243 quad_perm:[1,0,3,2] row_mask:0xf bank_mask:0xf
	v_bfi_b32 v248, v238, v244, v248
	v_bfi_b32 v249, v238, v245, v249
	v_bfi_b32 v250, v238, v246, v250
	v_bfi_b32 v251, v238, v247, v251
	v_bfi_b32 v244, v238, v68, v244
	v_bfi_b32 v245, v238, v69, v245
	v_bfi_b32 v246, v238, v70, v246
	v_bfi_b32 v247, v238, v71, v247
	global_store_dwordx4 v[216:217], v[248:251], off offset:-1536
	global_store_dwordx4 v[216:217], v[244:247], off offset:2560
	v_mov_b32_e32 v222, v72
	v_mov_b32_e32 v223, v73
	v_lshl_add_u64 v[226:227], v[90:91], 0, v[224:225]
	s_nop 0
	v_permlane32_swap_b32_e32 v220, v222
	v_permlane32_swap_b32_e32 v221, v223
	s_nop 1
	v_permlane16_swap_b32_e32 v220, v222
	v_permlane16_swap_b32_e32 v221, v223
	global_store_dwordx4 v[226:227], v[220:223], off offset:256
	global_load_dwordx4 v[68:71], v[180:181], off
	ds_read_b64 v[72:73], v33 offset:17408
	v_lshlrev_b64 v[74:75], 10, v[182:183]
	v_lshl_add_u64 v[74:75], v[74:75], 0, v[34:35]
	v_lshl_add_u64 v[74:75], v[74:75], 1, s[6:7]
	s_waitcnt lgkmcnt(0)
	v_pk_mul_f32 v[64:65], v[64:65], v[72:73] op_sel_hi:[1,0]
	v_pk_mul_f32 v[66:67], v[66:67], v[72:73] op_sel_hi:[1,0]
	v_pk_mul_f32 v[60:61], v[60:61], v[72:73] op_sel_hi:[1,0]
	v_pk_mul_f32 v[62:63], v[62:63], v[72:73] op_sel_hi:[1,0]
	v_pk_mul_f32 v[56:57], v[56:57], v[72:73] op_sel_hi:[1,0]
	v_pk_mul_f32 v[58:59], v[58:59], v[72:73] op_sel_hi:[1,0]
	v_pk_mul_f32 v[52:53], v[52:53], v[72:73] op_sel_hi:[1,0]
	v_pk_mul_f32 v[54:55], v[54:55], v[72:73] op_sel_hi:[1,0]
	s_waitcnt vmcnt(0)
	v_pk_fma_f32 v[64:65], v[144:145], v[64:65], v[68:69]
	v_pk_fma_f32 v[66:67], v[146:147], v[66:67], v[70:71]
	v_pk_mul_f32 v[68:69], v[72:73], v[64:65] op_sel:[1,0]
	v_pk_mul_f32 v[70:71], v[72:73], v[66:67] op_sel:[1,0]
	v_pk_mul_f32 v[68:69], v[152:153], v[68:69]
	v_pk_mul_f32 v[70:71], v[154:155], v[70:71]
	v_cvt_pk_bf16_f32 v68, v68, v69
	s_nop 0
	v_cvt_pk_bf16_f32 v69, v70, v71
	v_mov_b32_e32 v248, v64
	v_mov_b32_e32 v249, v65
	v_mov_b32_e32 v250, v66
	v_mov_b32_e32 v251, v67
	v_mov_b32_e32 v220, v68
	v_mov_b32_e32 v221, v69
	global_load_dwordx4 v[64:67], v[180:181], off offset:64
	s_waitcnt vmcnt(0)
	v_pk_fma_f32 v[60:61], v[140:141], v[60:61], v[64:65]
	v_pk_fma_f32 v[62:63], v[142:143], v[62:63], v[66:67]
	v_pk_mul_f32 v[64:65], v[72:73], v[60:61] op_sel:[1,0]
	v_pk_mul_f32 v[66:67], v[72:73], v[62:63] op_sel:[1,0]
	v_pk_mul_f32 v[64:65], v[156:157], v[64:65]
	v_pk_mul_f32 v[66:67], v[158:159], v[66:67]
	v_cvt_pk_bf16_f32 v64, v64, v65
	s_nop 0
	v_cvt_pk_bf16_f32 v65, v66, v67
	v_bfi_b32 v240, v238, v248, v60
	v_bfi_b32 v241, v238, v249, v61
	v_bfi_b32 v242, v238, v250, v62
	v_bfi_b32 v243, v238, v251, v63
	v_lshl_add_u64 v[216:217], v[180:181], 0, v[252:253]
	s_nop 0
	v_mov_b32_dpp v244, v240 quad_perm:[1,0,3,2] row_mask:0xf bank_mask:0xf
	v_mov_b32_dpp v245, v241 quad_perm:[1,0,3,2] row_mask:0xf bank_mask:0xf
	v_mov_b32_dpp v246, v242 quad_perm:[1,0,3,2] row_mask:0xf bank_mask:0xf
	v_mov_b32_dpp v247, v243 quad_perm:[1,0,3,2] row_mask:0xf bank_mask:0xf
	v_bfi_b32 v248, v238, v244, v248
	v_bfi_b32 v249, v238, v245, v249
	v_bfi_b32 v250, v238, v246, v250
	v_bfi_b32 v251, v238, v247, v251
	v_bfi_b32 v244, v238, v60, v244
	v_bfi_b32 v245, v238, v61, v245
	v_bfi_b32 v246, v238, v62, v246
	v_bfi_b32 v247, v238, v63, v247
	global_store_dwordx4 v[216:217], v[248:251], off offset:-2048
	global_store_dwordx4 v[216:217], v[244:247], off offset:2048
	v_mov_b32_e32 v222, v64
	v_mov_b32_e32 v223, v65
	v_lshl_add_u64 v[226:227], v[74:75], 0, v[224:225]
	s_nop 0
	v_permlane32_swap_b32_e32 v220, v222
	v_permlane32_swap_b32_e32 v221, v223
	s_nop 1
	v_permlane16_swap_b32_e32 v220, v222
	v_permlane16_swap_b32_e32 v221, v223
	global_store_dwordx4 v[226:227], v[220:223], off
	global_load_dwordx4 v[60:63], v[180:181], off offset:512
	s_waitcnt vmcnt(0)
	v_pk_fma_f32 v[56:57], v[136:137], v[56:57], v[60:61]
	v_pk_fma_f32 v[58:59], v[138:139], v[58:59], v[62:63]
	v_pk_mul_f32 v[60:61], v[72:73], v[56:57] op_sel:[1,0]
	v_pk_mul_f32 v[62:63], v[72:73], v[58:59] op_sel:[1,0]
	v_pk_mul_f32 v[60:61], v[148:149], v[60:61]
	v_pk_mul_f32 v[62:63], v[150:151], v[62:63]
	v_cvt_pk_bf16_f32 v60, v60, v61
	s_nop 0
	v_cvt_pk_bf16_f32 v61, v62, v63
	v_mov_b32_e32 v248, v56
	v_mov_b32_e32 v249, v57
	v_mov_b32_e32 v250, v58
	v_mov_b32_e32 v251, v59
	v_mov_b32_e32 v220, v60
	v_mov_b32_e32 v221, v61
	global_load_dwordx4 v[56:59], v[180:181], off offset:576
	s_waitcnt vmcnt(0)
; __device__ __forceinline__ unsigned cvt_pk_bf16(float lo, float hi) { unsigned r; asm volatile("v_cvt_pk_bf16_f32 %0, %1, %2" : "=v"(r) : "v"(lo), "v"(hi)); return r; }
;     __device__ __forceinline__ void fused(f32x4 (&acc)[2][2][4][2], const Unit& u, int wr, int wc, int fr, int fq, PG8_LAS unsigned char* lds, int wid, int lane) const {
;     ...
;         for (int ai = 0; ai < 2; ++ai)
; #pragma unroll
;             for (int m = 0; m < 4; ++m) { const int r = ai * HALF + wr * 64 + m * 16 + fr; const f32x2v sr = S[r]; const size_t off = (size_t)(u.pm * BM + r) * 1024 + col0;
; #pragma unroll
;                 for (int bj = 0; bj < 2; ++bj)
; #pragma unroll
;                     for (int n = 0; n < 2; ++n) { const f32x4 bs = *(const f32x4*)(base + off + bj * HALF + n * 16); const f32x4 x1 = bs + acc[ai][bj][m][n] * sr.x * gv[bj][n];
;                         const f32x4 o = x1 * sr.y * g2v[bj][n]; u32x2 w; w.x = cvt_pk_bf16(o[0], o[1]); w.y = cvt_pk_bf16(o[2], o[3]);
;                         if (!dry || x1[0] == 1.2345e38f) { *(f32x4*)(out + off + bj * HALF + n * 16) = x1; *(u32x2*)(xn + off + bj * HALF + n * 16) = w; } }
;                 if (m & 1) asm volatile("" ::: "memory"); }
	v_pk_fma_f32 v[52:53], v[132:133], v[52:53], v[56:57]
	v_pk_fma_f32 v[54:55], v[134:135], v[54:55], v[58:59]
	v_pk_mul_f32 v[56:57], v[72:73], v[52:53] op_sel:[1,0]
	v_pk_mul_f32 v[58:59], v[72:73], v[54:55] op_sel:[1,0]
	v_pk_mul_f32 v[56:57], v[128:129], v[56:57]
	v_pk_mul_f32 v[58:59], v[130:131], v[58:59]
	v_cvt_pk_bf16_f32 v56, v56, v57
	s_nop 0
	v_cvt_pk_bf16_f32 v57, v58, v59
	v_bfi_b32 v240, v238, v248, v52
	v_bfi_b32 v241, v238, v249, v53
	v_bfi_b32 v242, v238, v250, v54
	v_bfi_b32 v243, v238, v251, v55
	v_lshl_add_u64 v[216:217], v[180:181], 0, v[252:253]
	s_nop 0
	v_mov_b32_dpp v244, v240 quad_perm:[1,0,3,2] row_mask:0xf bank_mask:0xf
	v_mov_b32_dpp v245, v241 quad_perm:[1,0,3,2] row_mask:0xf bank_mask:0xf
	v_mov_b32_dpp v246, v242 quad_perm:[1,0,3,2] row_mask:0xf bank_mask:0xf
	v_mov_b32_dpp v247, v243 quad_perm:[1,0,3,2] row_mask:0xf bank_mask:0xf
	v_bfi_b32 v248, v238, v244, v248
	v_bfi_b32 v249, v238, v245, v249
	v_bfi_b32 v250, v238, v246, v250
	v_bfi_b32 v251, v238, v247, v251
	v_bfi_b32 v244, v238, v52, v244
	v_bfi_b32 v245, v238, v53, v245
	v_bfi_b32 v246, v238, v54, v246
	v_bfi_b32 v247, v238, v55, v247
	global_store_dwordx4 v[216:217], v[248:251], off offset:-1536
	global_store_dwordx4 v[216:217], v[244:247], off offset:2560
	v_mov_b32_e32 v222, v56
	v_mov_b32_e32 v223, v57
	v_lshl_add_u64 v[226:227], v[74:75], 0, v[224:225]
	s_nop 0
	v_permlane32_swap_b32_e32 v220, v222
	v_permlane32_swap_b32_e32 v221, v223
	s_nop 1
	v_permlane16_swap_b32_e32 v220, v222
	v_permlane16_swap_b32_e32 v221, v223
	global_store_dwordx4 v[226:227], v[220:223], off offset:256
	global_load_dwordx4 v[52:55], v[184:185], off
	ds_read_b64 v[56:57], v33 offset:17536
	v_lshlrev_b64 v[58:59], 10, v[186:187]
	v_lshl_add_u64 v[58:59], v[58:59], 0, v[34:35]
	v_lshl_add_u64 v[58:59], v[58:59], 1, s[6:7]
	s_waitcnt lgkmcnt(0)
	v_pk_mul_f32 v[48:49], v[48:49], v[56:57] op_sel_hi:[1,0]
	v_pk_mul_f32 v[50:51], v[50:51], v[56:57] op_sel_hi:[1,0]
	v_pk_mul_f32 v[44:45], v[44:45], v[56:57] op_sel_hi:[1,0]
	v_pk_mul_f32 v[46:47], v[46:47], v[56:57] op_sel_hi:[1,0]
	v_pk_mul_f32 v[40:41], v[40:41], v[56:57] op_sel_hi:[1,0]
	v_pk_mul_f32 v[42:43], v[42:43], v[56:57] op_sel_hi:[1,0]
	v_pk_mul_f32 v[36:37], v[36:37], v[56:57] op_sel_hi:[1,0]
	v_pk_mul_f32 v[38:39], v[38:39], v[56:57] op_sel_hi:[1,0]
	s_waitcnt vmcnt(0)
	v_pk_fma_f32 v[48:49], v[144:145], v[48:49], v[52:53]
	v_pk_fma_f32 v[50:51], v[146:147], v[50:51], v[54:55]
	v_pk_mul_f32 v[52:53], v[56:57], v[48:49] op_sel:[1,0]
	v_pk_mul_f32 v[54:55], v[56:57], v[50:51] op_sel:[1,0]
	v_pk_mul_f32 v[52:53], v[152:153], v[52:53]
	v_pk_mul_f32 v[54:55], v[154:155], v[54:55]
	v_cvt_pk_bf16_f32 v52, v52, v53
	s_nop 0
	v_cvt_pk_bf16_f32 v53, v54, v55
	v_mov_b32_e32 v248, v48
	v_mov_b32_e32 v249, v49
	v_mov_b32_e32 v250, v50
	v_mov_b32_e32 v251, v51
	v_mov_b32_e32 v220, v52
	v_mov_b32_e32 v221, v53
	global_load_dwordx4 v[48:51], v[184:185], off offset:64
	s_waitcnt vmcnt(0)
	v_pk_fma_f32 v[44:45], v[140:141], v[44:45], v[48:49]
	v_pk_fma_f32 v[46:47], v[142:143], v[46:47], v[50:51]
	v_pk_mul_f32 v[48:49], v[56:57], v[44:45] op_sel:[1,0]
	v_pk_mul_f32 v[50:51], v[56:57], v[46:47] op_sel:[1,0]
	v_pk_mul_f32 v[48:49], v[156:157], v[48:49]
	v_pk_mul_f32 v[50:51], v[158:159], v[50:51]
	v_cvt_pk_bf16_f32 v48, v48, v49
	s_nop 0
	v_cvt_pk_bf16_f32 v49, v50, v51
	v_bfi_b32 v240, v238, v248, v44
	v_bfi_b32 v241, v238, v249, v45
	v_bfi_b32 v242, v238, v250, v46
	v_bfi_b32 v243, v238, v251, v47
	v_lshl_add_u64 v[216:217], v[184:185], 0, v[252:253]
	s_nop 0
	v_mov_b32_dpp v244, v240 quad_perm:[1,0,3,2] row_mask:0xf bank_mask:0xf
	v_mov_b32_dpp v245, v241 quad_perm:[1,0,3,2] row_mask:0xf bank_mask:0xf
	v_mov_b32_dpp v246, v242 quad_perm:[1,0,3,2] row_mask:0xf bank_mask:0xf
	v_mov_b32_dpp v247, v243 quad_perm:[1,0,3,2] row_mask:0xf bank_mask:0xf
	v_bfi_b32 v248, v238, v244, v248
	v_bfi_b32 v249, v238, v245, v249
	v_bfi_b32 v250, v238, v246, v250
	v_bfi_b32 v251, v238, v247, v251
	v_bfi_b32 v244, v238, v44, v244
	v_bfi_b32 v245, v238, v45, v245
	v_bfi_b32 v246, v238, v46, v246
	v_bfi_b32 v247, v238, v47, v247
	global_store_dwordx4 v[216:217], v[248:251], off offset:-2048
	global_store_dwordx4 v[216:217], v[244:247], off offset:2048
	v_mov_b32_e32 v222, v48
	v_mov_b32_e32 v223, v49
	v_lshl_add_u64 v[226:227], v[58:59], 0, v[224:225]
	s_nop 0
	v_permlane32_swap_b32_e32 v220, v222
	v_permlane32_swap_b32_e32 v221, v223
	s_nop 1
	v_permlane16_swap_b32_e32 v220, v222
	v_permlane16_swap_b32_e32 v221, v223
	global_store_dwordx4 v[226:227], v[220:223], off
	global_load_dwordx4 v[44:47], v[184:185], off offset:512
	s_waitcnt vmcnt(0)
	v_pk_fma_f32 v[40:41], v[136:137], v[40:41], v[44:45]
	v_pk_fma_f32 v[42:43], v[138:139], v[42:43], v[46:47]
	v_pk_mul_f32 v[44:45], v[56:57], v[40:41] op_sel:[1,0]
	v_pk_mul_f32 v[46:47], v[56:57], v[42:43] op_sel:[1,0]
	v_pk_mul_f32 v[44:45], v[148:149], v[44:45]
	v_pk_mul_f32 v[46:47], v[150:151], v[46:47]
	v_cvt_pk_bf16_f32 v44, v44, v45
	s_nop 0
	v_cvt_pk_bf16_f32 v45, v46, v47
	v_mov_b32_e32 v248, v40
	v_mov_b32_e32 v249, v41
	v_mov_b32_e32 v250, v42
	v_mov_b32_e32 v251, v43
	v_mov_b32_e32 v220, v44
	v_mov_b32_e32 v221, v45
	global_load_dwordx4 v[40:43], v[184:185], off offset:576
	s_waitcnt vmcnt(0)
; __device__ __forceinline__ unsigned cvt_pk_bf16(float lo, float hi) { unsigned r; asm volatile("v_cvt_pk_bf16_f32 %0, %1, %2" : "=v"(r) : "v"(lo), "v"(hi)); return r; }
;     __device__ __forceinline__ void fused(f32x4 (&acc)[2][2][4][2], const Unit& u, int wr, int wc, int fr, int fq, PG8_LAS unsigned char* lds, int wid, int lane) const {
;     ...
;         for (int ai = 0; ai < 2; ++ai)
; #pragma unroll
;             for (int m = 0; m < 4; ++m) { const int r = ai * HALF + wr * 64 + m * 16 + fr; const f32x2v sr = S[r]; const size_t off = (size_t)(u.pm * BM + r) * 1024 + col0;
; #pragma unroll
;                 for (int bj = 0; bj < 2; ++bj)
; #pragma unroll
;                     for (int n = 0; n < 2; ++n) { const f32x4 bs = *(const f32x4*)(base + off + bj * HALF + n * 16); const f32x4 x1 = bs + acc[ai][bj][m][n] * sr.x * gv[bj][n];
;                         const f32x4 o = x1 * sr.y * g2v[bj][n]; u32x2 w; w.x = cvt_pk_bf16(o[0], o[1]); w.y = cvt_pk_bf16(o[2], o[3]);
;                         if (!dry || x1[0] == 1.2345e38f) { *(f32x4*)(out + off + bj * HALF + n * 16) = x1; *(u32x2*)(xn + off + bj * HALF + n * 16) = w; } }
;                 if (m & 1) asm volatile("" ::: "memory"); }
	v_pk_fma_f32 v[36:37], v[132:133], v[36:37], v[40:41]
	v_pk_fma_f32 v[38:39], v[134:135], v[38:39], v[42:43]
	v_pk_mul_f32 v[40:41], v[56:57], v[36:37] op_sel:[1,0]
	v_pk_mul_f32 v[42:43], v[56:57], v[38:39] op_sel:[1,0]
	v_pk_mul_f32 v[40:41], v[128:129], v[40:41]
	v_pk_mul_f32 v[42:43], v[130:131], v[42:43]
	v_cvt_pk_bf16_f32 v40, v40, v41
	s_nop 0
	v_cvt_pk_bf16_f32 v41, v42, v43
	v_bfi_b32 v240, v238, v248, v36
	v_bfi_b32 v241, v238, v249, v37
	v_bfi_b32 v242, v238, v250, v38
	v_bfi_b32 v243, v238, v251, v39
	v_lshl_add_u64 v[216:217], v[184:185], 0, v[252:253]
	s_nop 0
	v_mov_b32_dpp v244, v240 quad_perm:[1,0,3,2] row_mask:0xf bank_mask:0xf
	v_mov_b32_dpp v245, v241 quad_perm:[1,0,3,2] row_mask:0xf bank_mask:0xf
	v_mov_b32_dpp v246, v242 quad_perm:[1,0,3,2] row_mask:0xf bank_mask:0xf
	v_mov_b32_dpp v247, v243 quad_perm:[1,0,3,2] row_mask:0xf bank_mask:0xf
	v_bfi_b32 v248, v238, v244, v248
	v_bfi_b32 v249, v238, v245, v249
	v_bfi_b32 v250, v238, v246, v250
	v_bfi_b32 v251, v238, v247, v251
	v_bfi_b32 v244, v238, v36, v244
	v_bfi_b32 v245, v238, v37, v245
	v_bfi_b32 v246, v238, v38, v246
	v_bfi_b32 v247, v238, v39, v247
	global_store_dwordx4 v[216:217], v[248:251], off offset:-1536
	global_store_dwordx4 v[216:217], v[244:247], off offset:2560
	v_mov_b32_e32 v222, v40
	v_mov_b32_e32 v223, v41
	v_lshl_add_u64 v[226:227], v[58:59], 0, v[224:225]
	s_nop 0
	v_permlane32_swap_b32_e32 v220, v222
	v_permlane32_swap_b32_e32 v221, v223
	s_nop 1
	v_permlane16_swap_b32_e32 v220, v222
	v_permlane16_swap_b32_e32 v221, v223
	global_store_dwordx4 v[226:227], v[220:223], off offset:256
	global_load_dwordx4 v[36:39], v[188:189], off
	ds_read_b64 v[40:41], v33 offset:17664
	v_lshlrev_b64 v[42:43], 10, v[190:191]
	v_lshl_add_u64 v[42:43], v[42:43], 0, v[34:35]
	v_lshl_add_u64 v[42:43], v[42:43], 1, s[6:7]
	s_waitcnt lgkmcnt(0)
	v_pk_mul_f32 v[28:29], v[28:29], v[40:41] op_sel_hi:[1,0]
	v_pk_mul_f32 v[30:31], v[30:31], v[40:41] op_sel_hi:[1,0]
	v_pk_mul_f32 v[24:25], v[24:25], v[40:41] op_sel_hi:[1,0]
	v_pk_mul_f32 v[26:27], v[26:27], v[40:41] op_sel_hi:[1,0]
	v_pk_mul_f32 v[20:21], v[20:21], v[40:41] op_sel_hi:[1,0]
	v_pk_mul_f32 v[22:23], v[22:23], v[40:41] op_sel_hi:[1,0]
	v_pk_mul_f32 v[16:17], v[16:17], v[40:41] op_sel_hi:[1,0]
	v_pk_mul_f32 v[18:19], v[18:19], v[40:41] op_sel_hi:[1,0]
	s_waitcnt vmcnt(0)
	v_pk_fma_f32 v[28:29], v[144:145], v[28:29], v[36:37]
	v_pk_fma_f32 v[30:31], v[146:147], v[30:31], v[38:39]
	v_pk_mul_f32 v[36:37], v[40:41], v[28:29] op_sel:[1,0]
	v_pk_mul_f32 v[38:39], v[40:41], v[30:31] op_sel:[1,0]
	v_pk_mul_f32 v[36:37], v[152:153], v[36:37]
	v_pk_mul_f32 v[38:39], v[154:155], v[38:39]
	v_cvt_pk_bf16_f32 v36, v36, v37
	s_nop 0
	v_cvt_pk_bf16_f32 v37, v38, v39
	v_mov_b32_e32 v248, v28
	v_mov_b32_e32 v249, v29
	v_mov_b32_e32 v250, v30
	v_mov_b32_e32 v251, v31
	v_mov_b32_e32 v220, v36
	v_mov_b32_e32 v221, v37
	global_load_dwordx4 v[28:31], v[188:189], off offset:64
	s_waitcnt vmcnt(0)
	v_pk_fma_f32 v[24:25], v[140:141], v[24:25], v[28:29]
	v_pk_fma_f32 v[26:27], v[142:143], v[26:27], v[30:31]
	v_pk_mul_f32 v[28:29], v[40:41], v[24:25] op_sel:[1,0]
	v_pk_mul_f32 v[30:31], v[40:41], v[26:27] op_sel:[1,0]
	v_pk_mul_f32 v[28:29], v[156:157], v[28:29]
	v_pk_mul_f32 v[30:31], v[158:159], v[30:31]
	v_cvt_pk_bf16_f32 v28, v28, v29
	s_nop 0
	v_cvt_pk_bf16_f32 v29, v30, v31
	v_bfi_b32 v240, v238, v248, v24
	v_bfi_b32 v241, v238, v249, v25
	v_bfi_b32 v242, v238, v250, v26
	v_bfi_b32 v243, v238, v251, v27
	v_lshl_add_u64 v[216:217], v[188:189], 0, v[252:253]
	s_nop 0
	v_mov_b32_dpp v244, v240 quad_perm:[1,0,3,2] row_mask:0xf bank_mask:0xf
	v_mov_b32_dpp v245, v241 quad_perm:[1,0,3,2] row_mask:0xf bank_mask:0xf
	v_mov_b32_dpp v246, v242 quad_perm:[1,0,3,2] row_mask:0xf bank_mask:0xf
	v_mov_b32_dpp v247, v243 quad_perm:[1,0,3,2] row_mask:0xf bank_mask:0xf
	v_bfi_b32 v248, v238, v244, v248
	v_bfi_b32 v249, v238, v245, v249
	v_bfi_b32 v250, v238, v246, v250
	v_bfi_b32 v251, v238, v247, v251
	v_bfi_b32 v244, v238, v24, v244
	v_bfi_b32 v245, v238, v25, v245
	v_bfi_b32 v246, v238, v26, v246
	v_bfi_b32 v247, v238, v27, v247
	global_store_dwordx4 v[216:217], v[248:251], off offset:-2048
	global_store_dwordx4 v[216:217], v[244:247], off offset:2048
	v_mov_b32_e32 v222, v28
	v_mov_b32_e32 v223, v29
	v_lshl_add_u64 v[226:227], v[42:43], 0, v[224:225]
	s_nop 0
	v_permlane32_swap_b32_e32 v220, v222
	v_permlane32_swap_b32_e32 v221, v223
	s_nop 1
	v_permlane16_swap_b32_e32 v220, v222
	v_permlane16_swap_b32_e32 v221, v223
	global_store_dwordx4 v[226:227], v[220:223], off
	global_load_dwordx4 v[24:27], v[188:189], off offset:512
	s_waitcnt vmcnt(0)
	v_pk_fma_f32 v[20:21], v[136:137], v[20:21], v[24:25]
	v_pk_fma_f32 v[22:23], v[138:139], v[22:23], v[26:27]
	v_pk_mul_f32 v[24:25], v[40:41], v[20:21] op_sel:[1,0]
	v_pk_mul_f32 v[26:27], v[40:41], v[22:23] op_sel:[1,0]
	v_pk_mul_f32 v[24:25], v[148:149], v[24:25]
	v_pk_mul_f32 v[26:27], v[150:151], v[26:27]
	v_cvt_pk_bf16_f32 v24, v24, v25
	s_nop 0
	v_cvt_pk_bf16_f32 v25, v26, v27
	v_mov_b32_e32 v248, v20
	v_mov_b32_e32 v249, v21
	v_mov_b32_e32 v250, v22
	v_mov_b32_e32 v251, v23
	v_mov_b32_e32 v220, v24
	v_mov_b32_e32 v221, v25
	global_load_dwordx4 v[20:23], v[188:189], off offset:576
	s_waitcnt vmcnt(0)
; __device__ __forceinline__ unsigned cvt_pk_bf16(float lo, float hi) { unsigned r; asm volatile("v_cvt_pk_bf16_f32 %0, %1, %2" : "=v"(r) : "v"(lo), "v"(hi)); return r; }
;     __device__ __forceinline__ void fused(f32x4 (&acc)[2][2][4][2], const Unit& u, int wr, int wc, int fr, int fq, PG8_LAS unsigned char* lds, int wid, int lane) const {
;     ...
;         for (int ai = 0; ai < 2; ++ai)
; #pragma unroll
;             for (int m = 0; m < 4; ++m) { const int r = ai * HALF + wr * 64 + m * 16 + fr; const f32x2v sr = S[r]; const size_t off = (size_t)(u.pm * BM + r) * 1024 + col0;
; #pragma unroll
;                 for (int bj = 0; bj < 2; ++bj)
; #pragma unroll
;                     for (int n = 0; n < 2; ++n) { const f32x4 bs = *(const f32x4*)(base + off + bj * HALF + n * 16); const f32x4 x1 = bs + acc[ai][bj][m][n] * sr.x * gv[bj][n];
;                         const f32x4 o = x1 * sr.y * g2v[bj][n]; u32x2 w; w.x = cvt_pk_bf16(o[0], o[1]); w.y = cvt_pk_bf16(o[2], o[3]);
;                         if (!dry || x1[0] == 1.2345e38f) { *(f32x4*)(out + off + bj * HALF + n * 16) = x1; *(u32x2*)(xn + off + bj * HALF + n * 16) = w; } }
;                 if (m & 1) asm volatile("" ::: "memory"); }
	v_pk_fma_f32 v[16:17], v[132:133], v[16:17], v[20:21]
	v_pk_fma_f32 v[18:19], v[134:135], v[18:19], v[22:23]
	v_pk_mul_f32 v[20:21], v[40:41], v[16:17] op_sel:[1,0]
	v_pk_mul_f32 v[22:23], v[40:41], v[18:19] op_sel:[1,0]
	v_pk_mul_f32 v[20:21], v[128:129], v[20:21]
	v_pk_mul_f32 v[22:23], v[130:131], v[22:23]
	v_cvt_pk_bf16_f32 v20, v20, v21
	s_nop 0
	v_cvt_pk_bf16_f32 v21, v22, v23
	v_bfi_b32 v240, v238, v248, v16
	v_bfi_b32 v241, v238, v249, v17
	v_bfi_b32 v242, v238, v250, v18
	v_bfi_b32 v243, v238, v251, v19
	v_lshl_add_u64 v[216:217], v[188:189], 0, v[252:253]
	s_nop 0
	v_mov_b32_dpp v244, v240 quad_perm:[1,0,3,2] row_mask:0xf bank_mask:0xf
	v_mov_b32_dpp v245, v241 quad_perm:[1,0,3,2] row_mask:0xf bank_mask:0xf
	v_mov_b32_dpp v246, v242 quad_perm:[1,0,3,2] row_mask:0xf bank_mask:0xf
	v_mov_b32_dpp v247, v243 quad_perm:[1,0,3,2] row_mask:0xf bank_mask:0xf
	v_bfi_b32 v248, v238, v244, v248
	v_bfi_b32 v249, v238, v245, v249
	v_bfi_b32 v250, v238, v246, v250
	v_bfi_b32 v251, v238, v247, v251
	v_bfi_b32 v244, v238, v16, v244
	v_bfi_b32 v245, v238, v17, v245
	v_bfi_b32 v246, v238, v18, v246
	v_bfi_b32 v247, v238, v19, v247
	global_store_dwordx4 v[216:217], v[248:251], off offset:-1536
	global_store_dwordx4 v[216:217], v[244:247], off offset:2560
	v_mov_b32_e32 v222, v20
	v_mov_b32_e32 v223, v21
	v_lshl_add_u64 v[226:227], v[42:43], 0, v[224:225]
	s_nop 0
	v_permlane32_swap_b32_e32 v220, v222
	v_permlane32_swap_b32_e32 v221, v223
	s_nop 1
	v_permlane16_swap_b32_e32 v220, v222
	v_permlane16_swap_b32_e32 v221, v223
	global_store_dwordx4 v[226:227], v[220:223], off offset:256
	global_load_dwordx4 v[16:19], v[192:193], off
	ds_read_b64 v[20:21], v33 offset:17792
	v_lshlrev_b64 v[22:23], 10, v[204:205]
	v_lshl_add_u64 v[22:23], v[22:23], 0, v[34:35]
	v_lshl_add_u64 v[22:23], v[22:23], 1, s[6:7]
	s_waitcnt lgkmcnt(0)
	v_pk_mul_f32 v[12:13], v[12:13], v[20:21] op_sel_hi:[1,0]
	v_pk_mul_f32 v[14:15], v[14:15], v[20:21] op_sel_hi:[1,0]
	v_pk_mul_f32 v[8:9], v[8:9], v[20:21] op_sel_hi:[1,0]
	v_pk_mul_f32 v[10:11], v[10:11], v[20:21] op_sel_hi:[1,0]
	v_pk_mul_f32 v[4:5], v[4:5], v[20:21] op_sel_hi:[1,0]
	v_pk_mul_f32 v[6:7], v[6:7], v[20:21] op_sel_hi:[1,0]
	v_pk_mul_f32 v[0:1], v[0:1], v[20:21] op_sel_hi:[1,0]
	v_pk_mul_f32 v[2:3], v[2:3], v[20:21] op_sel_hi:[1,0]
	s_waitcnt vmcnt(0)
	v_pk_fma_f32 v[12:13], v[144:145], v[12:13], v[16:17]
	v_pk_fma_f32 v[14:15], v[146:147], v[14:15], v[18:19]
	v_pk_mul_f32 v[16:17], v[20:21], v[12:13] op_sel:[1,0]
	v_pk_mul_f32 v[18:19], v[20:21], v[14:15] op_sel:[1,0]
	v_pk_mul_f32 v[16:17], v[152:153], v[16:17]
	v_pk_mul_f32 v[18:19], v[154:155], v[18:19]
	v_cvt_pk_bf16_f32 v16, v16, v17
	s_nop 0
	v_cvt_pk_bf16_f32 v17, v18, v19
	v_mov_b32_e32 v248, v12
	v_mov_b32_e32 v249, v13
	v_mov_b32_e32 v250, v14
	v_mov_b32_e32 v251, v15
	v_mov_b32_e32 v220, v16
	v_mov_b32_e32 v221, v17
	global_load_dwordx4 v[12:15], v[192:193], off offset:64
	s_waitcnt vmcnt(0)
	v_pk_fma_f32 v[8:9], v[140:141], v[8:9], v[12:13]
	v_pk_fma_f32 v[10:11], v[142:143], v[10:11], v[14:15]
	v_pk_mul_f32 v[12:13], v[20:21], v[8:9] op_sel:[1,0]
	v_pk_mul_f32 v[14:15], v[20:21], v[10:11] op_sel:[1,0]
	v_pk_mul_f32 v[12:13], v[156:157], v[12:13]
	v_pk_mul_f32 v[14:15], v[158:159], v[14:15]
	v_cvt_pk_bf16_f32 v12, v12, v13
	s_nop 0
	v_cvt_pk_bf16_f32 v13, v14, v15
	v_bfi_b32 v240, v238, v248, v8
	v_bfi_b32 v241, v238, v249, v9
	v_bfi_b32 v242, v238, v250, v10
	v_bfi_b32 v243, v238, v251, v11
	v_lshl_add_u64 v[216:217], v[192:193], 0, v[252:253]
	s_nop 0
	v_mov_b32_dpp v244, v240 quad_perm:[1,0,3,2] row_mask:0xf bank_mask:0xf
	v_mov_b32_dpp v245, v241 quad_perm:[1,0,3,2] row_mask:0xf bank_mask:0xf
	v_mov_b32_dpp v246, v242 quad_perm:[1,0,3,2] row_mask:0xf bank_mask:0xf
	v_mov_b32_dpp v247, v243 quad_perm:[1,0,3,2] row_mask:0xf bank_mask:0xf
	v_bfi_b32 v248, v238, v244, v248
	v_bfi_b32 v249, v238, v245, v249
	v_bfi_b32 v250, v238, v246, v250
	v_bfi_b32 v251, v238, v247, v251
	v_bfi_b32 v244, v238, v8, v244
	v_bfi_b32 v245, v238, v9, v245
	v_bfi_b32 v246, v238, v10, v246
	v_bfi_b32 v247, v238, v11, v247
	global_store_dwordx4 v[216:217], v[248:251], off offset:-2048
	global_store_dwordx4 v[216:217], v[244:247], off offset:2048
	v_mov_b32_e32 v222, v12
	v_mov_b32_e32 v223, v13
	v_lshl_add_u64 v[226:227], v[22:23], 0, v[224:225]
	s_nop 0
	v_permlane32_swap_b32_e32 v220, v222
	v_permlane32_swap_b32_e32 v221, v223
	s_nop 1
	v_permlane16_swap_b32_e32 v220, v222
	v_permlane16_swap_b32_e32 v221, v223
	global_store_dwordx4 v[226:227], v[220:223], off
	global_load_dwordx4 v[8:11], v[192:193], off offset:512
	s_waitcnt vmcnt(0)
	v_pk_fma_f32 v[4:5], v[136:137], v[4:5], v[8:9]
	v_pk_fma_f32 v[6:7], v[138:139], v[6:7], v[10:11]
	v_pk_mul_f32 v[8:9], v[20:21], v[4:5] op_sel:[1,0]
	v_pk_mul_f32 v[10:11], v[20:21], v[6:7] op_sel:[1,0]
	v_pk_mul_f32 v[8:9], v[148:149], v[8:9]
	v_pk_mul_f32 v[10:11], v[150:151], v[10:11]
	v_cvt_pk_bf16_f32 v8, v8, v9
	s_nop 0
	v_cvt_pk_bf16_f32 v9, v10, v11
	v_mov_b32_e32 v248, v4
	v_mov_b32_e32 v249, v5
	v_mov_b32_e32 v250, v6
	v_mov_b32_e32 v251, v7
	v_mov_b32_e32 v220, v8
	v_mov_b32_e32 v221, v9
	global_load_dwordx4 v[4:7], v[192:193], off offset:576
	s_waitcnt vmcnt(0)
	v_pk_fma_f32 v[0:1], v[132:133], v[0:1], v[4:5]
	v_pk_fma_f32 v[2:3], v[134:135], v[2:3], v[6:7]
	v_pk_mul_f32 v[4:5], v[20:21], v[0:1] op_sel:[1,0]
	v_pk_mul_f32 v[6:7], v[20:21], v[2:3] op_sel:[1,0]
	v_pk_mul_f32 v[4:5], v[128:129], v[4:5]
	v_pk_mul_f32 v[6:7], v[130:131], v[6:7]
	v_cvt_pk_bf16_f32 v4, v4, v5
	s_nop 0
	v_cvt_pk_bf16_f32 v5, v6, v7
	v_bfi_b32 v240, v238, v248, v0
	v_bfi_b32 v241, v238, v249, v1
	v_bfi_b32 v242, v238, v250, v2
	v_bfi_b32 v243, v238, v251, v3
	v_lshl_add_u64 v[216:217], v[192:193], 0, v[252:253]
	s_nop 0
	v_mov_b32_dpp v244, v240 quad_perm:[1,0,3,2] row_mask:0xf bank_mask:0xf
	v_mov_b32_dpp v245, v241 quad_perm:[1,0,3,2] row_mask:0xf bank_mask:0xf
	v_mov_b32_dpp v246, v242 quad_perm:[1,0,3,2] row_mask:0xf bank_mask:0xf
	v_mov_b32_dpp v247, v243 quad_perm:[1,0,3,2] row_mask:0xf bank_mask:0xf
	v_bfi_b32 v248, v238, v244, v248
	v_bfi_b32 v249, v238, v245, v249
	v_bfi_b32 v250, v238, v246, v250
	v_bfi_b32 v251, v238, v247, v251
	v_bfi_b32 v244, v238, v0, v244
	v_bfi_b32 v245, v238, v1, v245
	v_bfi_b32 v246, v238, v2, v246
	v_bfi_b32 v247, v238, v3, v247
	global_store_dwordx4 v[216:217], v[248:251], off offset:-1536
	global_store_dwordx4 v[216:217], v[244:247], off offset:2560
	v_mov_b32_e32 v222, v4
	v_mov_b32_e32 v223, v5
	v_lshl_add_u64 v[226:227], v[22:23], 0, v[224:225]
	s_nop 0
	v_permlane32_swap_b32_e32 v220, v222
	v_permlane32_swap_b32_e32 v221, v223
	s_nop 1
	v_permlane16_swap_b32_e32 v220, v222
	v_permlane16_swap_b32_e32 v221, v223
	global_store_dwordx4 v[226:227], v[220:223], off offset:256
